# GEMM loops: dropped the back-to-back s_setprio 0 / s_setprio 1 pair in the middle of each 32-MFMA block
# speedup vs baseline: 1.0066x; 1.0041x over previous
; #define PG8_STAGE(bufoff, gbase, voff) do { _Pragma("unroll") for (int _i = 0; _i < 2; ++_i) \
;         __builtin_amdgcn_global_load_lds((const unsigned*)((const char*)(gbase) + (voff)[_i]), (LAS unsigned*)(lds + (bufoff) + ldsw + _i * 8192), 16, 0, 0); } while (0)
; #define PG8_LDA(dst, b, h) do { _Pragma("unroll") for (int m = 0; m < 4; ++m) _Pragma("unroll") for (int k = 0; k < 2; ++k) dst[m][k] = *(const LAS bf16x8*)(lds + PG8_SA(b, h) + aoff + m * 2048 + k * 1024); } while (0)
; #define PG8_LDB(dst, b, h) do { _Pragma("unroll") for (int n = 0; n < 2; ++n) _Pragma("unroll") for (int k = 0; k < 2; ++k) dst[n][k] = *(const LAS bf16x8*)(lds + PG8_SB(b, h) + boff + n * 2048 + k * 1024); } while (0)
; #define PG8_MMA(ai, bj, At, Bt) do { __builtin_amdgcn_s_setprio(1); _Pragma("unroll") for (int m = 0; m < 4; ++m) _Pragma("unroll") for (int n = 0; n < 2; ++n) _Pragma("unroll") for (int k = 0; k < 2; ++k) \
;         acc[ai][bj][m][n] = __builtin_amdgcn_mfma_f32_16x16x32_bf16(Bt[n][k], At[m][k], acc[ai][bj][m][n], 0, 0, 0); __builtin_amdgcn_s_setprio(0); } while (0)
; #define PG8_WAIT_V(n) asm volatile("s_waitcnt vmcnt(" #n ")" ::: "memory")
; #define PG8_WAIT_L(n) asm volatile("s_waitcnt lgkmcnt(" #n ")" ::: "memory")
; #define PG8_BAR __builtin_amdgcn_s_barrier()
; #define PG8_SCHED __builtin_amdgcn_sched_barrier(0)
; __device__ __forceinline__ void gemm_phase(LAS unsigned char* lds, const Params& p, const bf16_t* gA, const bf16_t* gBt, const int gM, const int gN, const int gK, const int epi, const int perm, bf16_t* const Hp, const int goff, const float coef) {
;     ...
;             PG8_LDB(B0, 0, 0); PG8_LDB(B1, 0, 1); PG8_SCHED; PG8_LDA(At, 0, 0); PG8_STAGE(PG8_SA(1, 1), a1 + hstep, voffA);
;             PG8_WAIT_V(8); PG8_WAIT_L(0); PG8_BAR; PG8_MMA(0, 0, At, B0); PG8_MMA(0, 1, At, B1); PG8_BAR; PG8_SCHED;
;             PG8_LDA(At, 0, 1); PG8_STAGE(PG8_SB(0, 0), b2, voffB); PG8_STAGE(PG8_SB(0, 1), b2 + hstep, voffB); PG8_STAGE(PG8_SA(0, 0), a2, voffA);
;             PG8_WAIT_V(8); PG8_WAIT_L(0); PG8_BAR; PG8_MMA(1, 0, At, B0); PG8_MMA(1, 1, At, B1); PG8_BAR; PG8_SCHED;
.LBB0_170:
	ds_read_b128 v[158:161], v155
	ds_read_b128 v[162:165], v155 offset:1024
	ds_read_b128 v[166:169], v155 offset:2048
	ds_read_b128 v[170:173], v155 offset:3072
	ds_read_b128 v[174:177], v156
	ds_read_b128 v[178:181], v156 offset:1024
	ds_read_b128 v[182:185], v156 offset:2048
	ds_read_b128 v[186:189], v156 offset:3072
	s_add_i32 s56, s48, 2
	s_add_u32 s46, s44, 0xfff80080
	s_addc_u32 s47, s45, -1
	s_cmp_eq_u32 s53, s48
	s_cselect_b32 s48, s50, s46
	s_cselect_b32 s49, s25, s47
	s_cselect_b32 s47, s27, s55
	s_cselect_b32 s46, s51, s54
	v_lshl_add_u64 v[144:145], s[44:45], 0, v[136:137]
	s_add_i32 m0, s14, 0xc000
	ds_read_b128 v[190:193], v157
	ds_read_b128 v[194:197], v157 offset:1024
	ds_read_b128 v[198:201], v157 offset:2048
	ds_read_b128 v[202:205], v157 offset:3072
	ds_read_b128 v[206:209], v157 offset:4096
	ds_read_b128 v[210:213], v157 offset:5120
	ds_read_b128 v[214:217], v157 offset:6144
	ds_read_b128 v[218:221], v157 offset:7168
	global_load_lds_dwordx4 v[144:145], off
	v_lshl_add_u64 v[144:145], s[44:45], 0, v[138:139]
	s_add_i32 m0, s14, 0xe000
	s_nop 0
	global_load_lds_dwordx4 v[144:145], off
	s_waitcnt vmcnt(8)
	s_waitcnt lgkmcnt(0)
	s_barrier
	s_setprio 1
	s_waitcnt lgkmcnt(0)
	v_mfma_f32_16x16x32_bf16 v[124:127], v[158:161], v[190:193], v[124:127]
	v_mfma_f32_16x16x32_bf16 v[120:123], v[166:169], v[190:193], v[120:123]
	v_mfma_f32_16x16x32_bf16 v[108:111], v[158:161], v[198:201], v[108:111]
	v_mfma_f32_16x16x32_bf16 v[104:107], v[166:169], v[198:201], v[104:107]
	v_mfma_f32_16x16x32_bf16 v[92:95], v[158:161], v[206:209], v[92:95]
	v_mfma_f32_16x16x32_bf16 v[88:91], v[166:169], v[206:209], v[88:91]
	v_mfma_f32_16x16x32_bf16 v[76:79], v[158:161], v[214:217], v[76:79]
	v_mfma_f32_16x16x32_bf16 v[72:75], v[166:169], v[214:217], v[72:75]
	v_mfma_f32_16x16x32_bf16 v[124:127], v[162:165], v[194:197], v[124:127]
	v_mfma_f32_16x16x32_bf16 v[120:123], v[170:173], v[194:197], v[120:123]
	v_mfma_f32_16x16x32_bf16 v[108:111], v[162:165], v[202:205], v[108:111]
	v_mfma_f32_16x16x32_bf16 v[104:107], v[170:173], v[202:205], v[104:107]
	v_mfma_f32_16x16x32_bf16 v[92:95], v[162:165], v[210:213], v[92:95]
	v_mfma_f32_16x16x32_bf16 v[88:91], v[170:173], v[210:213], v[88:91]
	v_mfma_f32_16x16x32_bf16 v[76:79], v[162:165], v[218:221], v[76:79]
	v_mfma_f32_16x16x32_bf16 v[72:75], v[170:173], v[218:221], v[72:75]
	v_mfma_f32_16x16x32_bf16 v[116:119], v[174:177], v[190:193], v[116:119]
	v_mfma_f32_16x16x32_bf16 v[112:115], v[182:185], v[190:193], v[112:115]
	v_mfma_f32_16x16x32_bf16 v[100:103], v[174:177], v[198:201], v[100:103]
	v_mfma_f32_16x16x32_bf16 v[96:99], v[182:185], v[198:201], v[96:99]
	v_mfma_f32_16x16x32_bf16 v[84:87], v[174:177], v[206:209], v[84:87]
	v_mfma_f32_16x16x32_bf16 v[80:83], v[182:185], v[206:209], v[80:83]
	v_mfma_f32_16x16x32_bf16 v[68:71], v[174:177], v[214:217], v[68:71]
	v_mfma_f32_16x16x32_bf16 v[64:67], v[182:185], v[214:217], v[64:67]
	v_mfma_f32_16x16x32_bf16 v[116:119], v[178:181], v[194:197], v[116:119]
	v_mfma_f32_16x16x32_bf16 v[112:115], v[186:189], v[194:197], v[112:115]
	v_mfma_f32_16x16x32_bf16 v[100:103], v[178:181], v[202:205], v[100:103]
	v_mfma_f32_16x16x32_bf16 v[96:99], v[186:189], v[202:205], v[96:99]
	v_mfma_f32_16x16x32_bf16 v[84:87], v[178:181], v[210:213], v[84:87]
	v_mfma_f32_16x16x32_bf16 v[80:83], v[186:189], v[210:213], v[80:83]
	v_mfma_f32_16x16x32_bf16 v[68:71], v[178:181], v[218:221], v[68:71]
	v_mfma_f32_16x16x32_bf16 v[64:67], v[186:189], v[218:221], v[64:67]
	s_setprio 0
	s_barrier
	s_add_i32 s57, s23, s11
	v_lshl_add_u64 v[144:145], s[46:47], 0, v[130:131]
	s_mov_b32 m0, s57
	ds_read_b128 v[190:193], v157 offset:16384
	ds_read_b128 v[194:197], v157 offset:17408
	ds_read_b128 v[198:201], v157 offset:18432
	ds_read_b128 v[202:205], v157 offset:19456
	ds_read_b128 v[206:209], v157 offset:20480
	ds_read_b128 v[210:213], v157 offset:21504
	ds_read_b128 v[214:217], v157 offset:22528
	ds_read_b128 v[218:221], v157 offset:23552
	global_load_lds_dwordx4 v[144:145], off
	s_add_i32 m0, s57, 0x2000
	s_add_u32 s58, s46, 0x80000
	v_lshl_add_u64 v[222:223], s[46:47], 0, v[134:135]
	s_addc_u32 s59, s47, 0
	s_add_i32 s57, s33, s11
	global_load_lds_dwordx4 v[222:223], off
	v_lshl_add_u64 v[224:225], s[58:59], 0, v[130:131]
	s_mov_b32 m0, s57
	v_lshl_add_u64 v[226:227], s[48:49], 0, v[132:133]
	global_load_lds_dwordx4 v[224:225], off
	v_lshl_add_u64 v[224:225], s[58:59], 0, v[134:135]
	s_add_i32 m0, s57, 0x2000
	s_nop 0
	global_load_lds_dwordx4 v[224:225], off
	v_lshl_add_u64 v[224:225], s[48:49], 0, v[128:129]
	s_mov_b32 m0, s14
	s_nop 0
	global_load_lds_dwordx4 v[224:225], off
	s_mov_b32 m0, s15
	s_nop 0
	global_load_lds_dwordx4 v[226:227], off
	s_waitcnt vmcnt(8)
	s_waitcnt lgkmcnt(0)
	s_barrier
; #define PG8_STAGE(bufoff, gbase, voff) do { _Pragma("unroll") for (int _i = 0; _i < 2; ++_i) \
;         __builtin_amdgcn_global_load_lds((const unsigned*)((const char*)(gbase) + (voff)[_i]), (LAS unsigned*)(lds + (bufoff) + ldsw + _i * 8192), 16, 0, 0); } while (0)
; #define PG8_LDA(dst, b, h) do { _Pragma("unroll") for (int m = 0; m < 4; ++m) _Pragma("unroll") for (int k = 0; k < 2; ++k) dst[m][k] = *(const LAS bf16x8*)(lds + PG8_SA(b, h) + aoff + m * 2048 + k * 1024); } while (0)
; #define PG8_LDB(dst, b, h) do { _Pragma("unroll") for (int n = 0; n < 2; ++n) _Pragma("unroll") for (int k = 0; k < 2; ++k) dst[n][k] = *(const LAS bf16x8*)(lds + PG8_SB(b, h) + boff + n * 2048 + k * 1024); } while (0)
; #define PG8_MMA(ai, bj, At, Bt) do { __builtin_amdgcn_s_setprio(1); _Pragma("unroll") for (int m = 0; m < 4; ++m) _Pragma("unroll") for (int n = 0; n < 2; ++n) _Pragma("unroll") for (int k = 0; k < 2; ++k) \
;         acc[ai][bj][m][n] = __builtin_amdgcn_mfma_f32_16x16x32_bf16(Bt[n][k], At[m][k], acc[ai][bj][m][n], 0, 0, 0); __builtin_amdgcn_s_setprio(0); } while (0)
; #define PG8_WAIT_V(n) asm volatile("s_waitcnt vmcnt(" #n ")" ::: "memory")
; #define PG8_WAIT_L(n) asm volatile("s_waitcnt lgkmcnt(" #n ")" ::: "memory")
; #define PG8_BAR __builtin_amdgcn_s_barrier()
; #define PG8_SCHED __builtin_amdgcn_sched_barrier(0)
; __device__ __forceinline__ void gemm_phase(LAS unsigned char* lds, const Params& p, const bf16_t* gA, const bf16_t* gBt, const int gM, const int gN, const int gK, const int epi, const int perm, bf16_t* const Hp, const int goff, const float coef) {
;     ...
;             PG8_WAIT_V(8); PG8_WAIT_L(0); PG8_BAR; PG8_MMA(1, 0, At, B0); PG8_MMA(1, 1, At, B1); PG8_BAR; PG8_SCHED;
;             PG8_LDB(B0, 1, 0); PG8_LDB(B1, 1, 1); PG8_SCHED; PG8_LDA(At, 1, 0); PG8_STAGE(PG8_SA(0, 1), a2 + hstep, voffA);
;             PG8_WAIT_V(8); PG8_WAIT_L(0); PG8_BAR; PG8_MMA(0, 0, At, B0); PG8_MMA(0, 1, At, B1); PG8_BAR; PG8_SCHED;
	s_setprio 1
	s_waitcnt lgkmcnt(0)
	v_mfma_f32_16x16x32_bf16 v[60:63], v[158:161], v[190:193], v[60:63]
	v_mfma_f32_16x16x32_bf16 v[56:59], v[166:169], v[190:193], v[56:59]
	v_mfma_f32_16x16x32_bf16 v[44:47], v[158:161], v[198:201], v[44:47]
	v_mfma_f32_16x16x32_bf16 v[40:43], v[166:169], v[198:201], v[40:43]
	v_mfma_f32_16x16x32_bf16 v[28:31], v[158:161], v[206:209], v[28:31]
	v_mfma_f32_16x16x32_bf16 v[24:27], v[166:169], v[206:209], v[24:27]
	v_mfma_f32_16x16x32_bf16 v[12:15], v[158:161], v[214:217], v[12:15]
	v_mfma_f32_16x16x32_bf16 v[8:11], v[166:169], v[214:217], v[8:11]
	v_mfma_f32_16x16x32_bf16 v[60:63], v[162:165], v[194:197], v[60:63]
	v_mfma_f32_16x16x32_bf16 v[56:59], v[170:173], v[194:197], v[56:59]
	v_mfma_f32_16x16x32_bf16 v[44:47], v[162:165], v[202:205], v[44:47]
	v_mfma_f32_16x16x32_bf16 v[40:43], v[170:173], v[202:205], v[40:43]
	v_mfma_f32_16x16x32_bf16 v[28:31], v[162:165], v[210:213], v[28:31]
	v_mfma_f32_16x16x32_bf16 v[24:27], v[170:173], v[210:213], v[24:27]
	v_mfma_f32_16x16x32_bf16 v[12:15], v[162:165], v[218:221], v[12:15]
	v_mfma_f32_16x16x32_bf16 v[8:11], v[170:173], v[218:221], v[8:11]
	v_mfma_f32_16x16x32_bf16 v[52:55], v[174:177], v[190:193], v[52:55]
	v_mfma_f32_16x16x32_bf16 v[48:51], v[182:185], v[190:193], v[48:51]
	v_mfma_f32_16x16x32_bf16 v[36:39], v[174:177], v[198:201], v[36:39]
	v_mfma_f32_16x16x32_bf16 v[32:35], v[182:185], v[198:201], v[32:35]
	v_mfma_f32_16x16x32_bf16 v[20:23], v[174:177], v[206:209], v[20:23]
	v_mfma_f32_16x16x32_bf16 v[16:19], v[182:185], v[206:209], v[16:19]
	v_mfma_f32_16x16x32_bf16 v[4:7], v[174:177], v[214:217], v[4:7]
	v_mfma_f32_16x16x32_bf16 v[0:3], v[182:185], v[214:217], v[0:3]
	v_mfma_f32_16x16x32_bf16 v[52:55], v[178:181], v[194:197], v[52:55]
	v_mfma_f32_16x16x32_bf16 v[48:51], v[186:189], v[194:197], v[48:51]
	v_mfma_f32_16x16x32_bf16 v[36:39], v[178:181], v[202:205], v[36:39]
	v_mfma_f32_16x16x32_bf16 v[32:35], v[186:189], v[202:205], v[32:35]
	v_mfma_f32_16x16x32_bf16 v[20:23], v[178:181], v[210:213], v[20:23]
	v_mfma_f32_16x16x32_bf16 v[16:19], v[186:189], v[210:213], v[16:19]
	v_mfma_f32_16x16x32_bf16 v[4:7], v[178:181], v[218:221], v[4:7]
	v_mfma_f32_16x16x32_bf16 v[0:3], v[186:189], v[218:221], v[0:3]
	s_setprio 0
	s_barrier
	s_add_i32 s57, 0, 0x18000
	s_add_i32 s58, 0, 0x1c000
	v_add_u32_e32 v170, s57, v146
	v_add_u32_e32 v186, s58, v146
	ds_read_b128 v[158:161], v170
	ds_read_b128 v[162:165], v170 offset:1024
	ds_read_b128 v[166:169], v170 offset:2048
	ds_read_b128 v[170:173], v170 offset:3072
	ds_read_b128 v[174:177], v186
	ds_read_b128 v[178:181], v186 offset:1024
	ds_read_b128 v[182:185], v186 offset:2048
	ds_read_b128 v[186:189], v186 offset:3072
	s_add_u32 s48, s48, 0x80000
	s_addc_u32 s49, s49, 0
	s_mov_b32 m0, s16
	v_lshl_add_u64 v[228:229], s[48:49], 0, v[128:129]
	ds_read_b128 v[190:193], v157 offset:32768
	ds_read_b128 v[194:197], v157 offset:33792
	ds_read_b128 v[198:201], v157 offset:34816
	ds_read_b128 v[202:205], v157 offset:35840
	ds_read_b128 v[206:209], v157 offset:36864
	ds_read_b128 v[210:213], v157 offset:37888
	ds_read_b128 v[214:217], v157 offset:38912
	ds_read_b128 v[218:221], v157 offset:39936
	global_load_lds_dwordx4 v[228:229], off
	v_lshl_add_u64 v[228:229], s[48:49], 0, v[132:133]
	s_mov_b32 m0, s17
	s_nop 0
	global_load_lds_dwordx4 v[228:229], off
	s_waitcnt vmcnt(8)
	s_waitcnt lgkmcnt(0)
	s_barrier
	s_setprio 1
	s_waitcnt lgkmcnt(0)
	v_mfma_f32_16x16x32_bf16 v[124:127], v[158:161], v[190:193], v[124:127]
	v_mfma_f32_16x16x32_bf16 v[120:123], v[166:169], v[190:193], v[120:123]
	v_mfma_f32_16x16x32_bf16 v[108:111], v[158:161], v[198:201], v[108:111]
	v_mfma_f32_16x16x32_bf16 v[104:107], v[166:169], v[198:201], v[104:107]
	v_mfma_f32_16x16x32_bf16 v[92:95], v[158:161], v[206:209], v[92:95]
	v_mfma_f32_16x16x32_bf16 v[88:91], v[166:169], v[206:209], v[88:91]
	v_mfma_f32_16x16x32_bf16 v[76:79], v[158:161], v[214:217], v[76:79]
	v_mfma_f32_16x16x32_bf16 v[72:75], v[166:169], v[214:217], v[72:75]
	v_mfma_f32_16x16x32_bf16 v[124:127], v[162:165], v[194:197], v[124:127]
	v_mfma_f32_16x16x32_bf16 v[120:123], v[170:173], v[194:197], v[120:123]
	v_mfma_f32_16x16x32_bf16 v[108:111], v[162:165], v[202:205], v[108:111]
	v_mfma_f32_16x16x32_bf16 v[104:107], v[170:173], v[202:205], v[104:107]
	v_mfma_f32_16x16x32_bf16 v[92:95], v[162:165], v[210:213], v[92:95]
	v_mfma_f32_16x16x32_bf16 v[88:91], v[170:173], v[210:213], v[88:91]
	v_mfma_f32_16x16x32_bf16 v[76:79], v[162:165], v[218:221], v[76:79]
	v_mfma_f32_16x16x32_bf16 v[72:75], v[170:173], v[218:221], v[72:75]
	v_mfma_f32_16x16x32_bf16 v[116:119], v[174:177], v[190:193], v[116:119]
	v_mfma_f32_16x16x32_bf16 v[112:115], v[182:185], v[190:193], v[112:115]
	v_mfma_f32_16x16x32_bf16 v[100:103], v[174:177], v[198:201], v[100:103]
	v_mfma_f32_16x16x32_bf16 v[96:99], v[182:185], v[198:201], v[96:99]
	v_mfma_f32_16x16x32_bf16 v[84:87], v[174:177], v[206:209], v[84:87]
	v_mfma_f32_16x16x32_bf16 v[80:83], v[182:185], v[206:209], v[80:83]
	v_mfma_f32_16x16x32_bf16 v[68:71], v[174:177], v[214:217], v[68:71]
	v_mfma_f32_16x16x32_bf16 v[64:67], v[182:185], v[214:217], v[64:67]
	v_mfma_f32_16x16x32_bf16 v[116:119], v[178:181], v[194:197], v[116:119]
	v_mfma_f32_16x16x32_bf16 v[112:115], v[186:189], v[194:197], v[112:115]
	v_mfma_f32_16x16x32_bf16 v[100:103], v[178:181], v[202:205], v[100:103]
	v_mfma_f32_16x16x32_bf16 v[96:99], v[186:189], v[202:205], v[96:99]
	v_mfma_f32_16x16x32_bf16 v[84:87], v[178:181], v[210:213], v[84:87]
	v_mfma_f32_16x16x32_bf16 v[80:83], v[186:189], v[210:213], v[80:83]
	v_mfma_f32_16x16x32_bf16 v[68:71], v[178:181], v[218:221], v[68:71]
	v_mfma_f32_16x16x32_bf16 v[64:67], v[186:189], v[218:221], v[64:67]
	s_setprio 0
	s_barrier
; #define PG8_STAGE(bufoff, gbase, voff) do { _Pragma("unroll") for (int _i = 0; _i < 2; ++_i) \
;         __builtin_amdgcn_global_load_lds((const unsigned*)((const char*)(gbase) + (voff)[_i]), (LAS unsigned*)(lds + (bufoff) + ldsw + _i * 8192), 16, 0, 0); } while (0)
; #define PG8_LDA(dst, b, h) do { _Pragma("unroll") for (int m = 0; m < 4; ++m) _Pragma("unroll") for (int k = 0; k < 2; ++k) dst[m][k] = *(const LAS bf16x8*)(lds + PG8_SA(b, h) + aoff + m * 2048 + k * 1024); } while (0)
; #define PG8_MMA(ai, bj, At, Bt) do { __builtin_amdgcn_s_setprio(1); _Pragma("unroll") for (int m = 0; m < 4; ++m) _Pragma("unroll") for (int n = 0; n < 2; ++n) _Pragma("unroll") for (int k = 0; k < 2; ++k) \
;         acc[ai][bj][m][n] = __builtin_amdgcn_mfma_f32_16x16x32_bf16(Bt[n][k], At[m][k], acc[ai][bj][m][n], 0, 0, 0); __builtin_amdgcn_s_setprio(0); } while (0)
; #define PG8_WAIT_V(n) asm volatile("s_waitcnt vmcnt(" #n ")" ::: "memory")
; #define PG8_WAIT_L(n) asm volatile("s_waitcnt lgkmcnt(" #n ")" ::: "memory")
; #define PG8_BAR __builtin_amdgcn_s_barrier()
; #define PG8_SCHED __builtin_amdgcn_sched_barrier(0)
; __device__ __forceinline__ void gemm_phase(LAS unsigned char* lds, const Params& p, const bf16_t* gA, const bf16_t* gBt, const int gM, const int gN, const int gK, const int epi, const int perm, bf16_t* const Hp, const int goff, const float coef) {
;     ...
;             PG8_LDA(At, 1, 1); PG8_STAGE(PG8_SB(1, 0), b3, voffB); PG8_STAGE(PG8_SB(1, 1), b3 + hstep, voffB); PG8_STAGE(PG8_SA(1, 0), a3, voffA);
;             PG8_WAIT_V(8); PG8_WAIT_L(0); PG8_BAR; PG8_MMA(1, 0, At, B0); PG8_MMA(1, 1, At, B1); PG8_BAR; PG8_SCHED;
;         }
;         if (wr == 0) PG8_BAR;
	s_add_i32 s48, s57, s11
	v_lshl_add_u64 v[144:145], v[144:145], 0, s[8:9]
	s_mov_b32 m0, s48
	ds_read_b128 v[190:193], v157 offset:49152
	ds_read_b128 v[194:197], v157 offset:50176
	ds_read_b128 v[198:201], v157 offset:51200
	ds_read_b128 v[202:205], v157 offset:52224
	ds_read_b128 v[206:209], v157 offset:53248
	ds_read_b128 v[210:213], v157 offset:54272
	ds_read_b128 v[214:217], v157 offset:55296
	ds_read_b128 v[218:221], v157 offset:56320
	global_load_lds_dwordx4 v[144:145], off
	s_add_i32 m0, s48, 0x2000
	s_add_u32 s46, s46, 0x80080
	v_lshl_add_u64 v[144:145], v[222:223], 0, s[8:9]
	s_addc_u32 s47, s47, 0
	s_add_i32 s48, s58, s11
	global_load_lds_dwordx4 v[144:145], off
	v_lshl_add_u64 v[144:145], s[46:47], 0, v[130:131]
	s_mov_b32 m0, s48
	s_nop 0
	global_load_lds_dwordx4 v[144:145], off
	v_lshl_add_u64 v[144:145], s[46:47], 0, v[134:135]
	s_add_i32 m0, s48, 0x2000
	s_nop 0
	global_load_lds_dwordx4 v[144:145], off
	v_lshl_add_u64 v[144:145], v[224:225], 0, s[8:9]
	s_mov_b32 m0, s19
	s_nop 0
	global_load_lds_dwordx4 v[144:145], off
	v_lshl_add_u64 v[144:145], v[226:227], 0, s[8:9]
	s_mov_b32 m0, s20
	s_nop 0
	global_load_lds_dwordx4 v[144:145], off
	s_waitcnt vmcnt(8)
	s_waitcnt lgkmcnt(0)
	s_barrier
	s_setprio 1
	s_waitcnt lgkmcnt(0)
	v_mfma_f32_16x16x32_bf16 v[60:63], v[158:161], v[190:193], v[60:63]
	v_mfma_f32_16x16x32_bf16 v[56:59], v[166:169], v[190:193], v[56:59]
	v_mfma_f32_16x16x32_bf16 v[44:47], v[158:161], v[198:201], v[44:47]
	v_mfma_f32_16x16x32_bf16 v[40:43], v[166:169], v[198:201], v[40:43]
	v_mfma_f32_16x16x32_bf16 v[28:31], v[158:161], v[206:209], v[28:31]
	v_mfma_f32_16x16x32_bf16 v[24:27], v[166:169], v[206:209], v[24:27]
	v_mfma_f32_16x16x32_bf16 v[12:15], v[158:161], v[214:217], v[12:15]
	v_mfma_f32_16x16x32_bf16 v[8:11], v[166:169], v[214:217], v[8:11]
	v_mfma_f32_16x16x32_bf16 v[60:63], v[162:165], v[194:197], v[60:63]
	v_mfma_f32_16x16x32_bf16 v[56:59], v[170:173], v[194:197], v[56:59]
	v_mfma_f32_16x16x32_bf16 v[44:47], v[162:165], v[202:205], v[44:47]
	v_mfma_f32_16x16x32_bf16 v[40:43], v[170:173], v[202:205], v[40:43]
	v_mfma_f32_16x16x32_bf16 v[28:31], v[162:165], v[210:213], v[28:31]
	v_mfma_f32_16x16x32_bf16 v[24:27], v[170:173], v[210:213], v[24:27]
	v_mfma_f32_16x16x32_bf16 v[12:15], v[162:165], v[218:221], v[12:15]
	v_mfma_f32_16x16x32_bf16 v[8:11], v[170:173], v[218:221], v[8:11]
	v_mfma_f32_16x16x32_bf16 v[52:55], v[174:177], v[190:193], v[52:55]
	v_mfma_f32_16x16x32_bf16 v[48:51], v[182:185], v[190:193], v[48:51]
	v_mfma_f32_16x16x32_bf16 v[36:39], v[174:177], v[198:201], v[36:39]
	v_mfma_f32_16x16x32_bf16 v[32:35], v[182:185], v[198:201], v[32:35]
	v_mfma_f32_16x16x32_bf16 v[20:23], v[174:177], v[206:209], v[20:23]
	v_mfma_f32_16x16x32_bf16 v[16:19], v[182:185], v[206:209], v[16:19]
	v_mfma_f32_16x16x32_bf16 v[4:7], v[174:177], v[214:217], v[4:7]
	v_mfma_f32_16x16x32_bf16 v[0:3], v[182:185], v[214:217], v[0:3]
	v_mfma_f32_16x16x32_bf16 v[52:55], v[178:181], v[194:197], v[52:55]
	v_mfma_f32_16x16x32_bf16 v[48:51], v[186:189], v[194:197], v[48:51]
	v_mfma_f32_16x16x32_bf16 v[36:39], v[178:181], v[202:205], v[36:39]
	v_mfma_f32_16x16x32_bf16 v[32:35], v[186:189], v[202:205], v[32:35]
	v_mfma_f32_16x16x32_bf16 v[20:23], v[178:181], v[210:213], v[20:23]
	v_mfma_f32_16x16x32_bf16 v[16:19], v[186:189], v[210:213], v[16:19]
	v_mfma_f32_16x16x32_bf16 v[4:7], v[178:181], v[218:221], v[4:7]
	v_mfma_f32_16x16x32_bf16 v[0:3], v[186:189], v[218:221], v[0:3]
	s_setprio 0
	s_barrier
	s_add_u32 s44, s44, 0x100
	s_addc_u32 s45, s45, 0
	s_add_u32 s54, s54, 0x100
	s_addc_u32 s55, s55, 0
	s_cmp_ge_u32 s56, s52
	s_mov_b32 s48, s56
	s_cbranch_scc0 .LBB0_170
	s_and_b64 vcc, exec, s[12:13]
	s_cbranch_vccz .LBB0_173
	s_barrier

; #define PG8_STAGE(bufoff, gbase, voff) do { _Pragma("unroll") for (int _i = 0; _i < 2; ++_i) \
;         __builtin_amdgcn_global_load_lds((const unsigned*)((const char*)(gbase) + (voff)[_i]), (LAS unsigned*)(lds + (bufoff) + ldsw + _i * 8192), 16, 0, 0); } while (0)
; #define PG8_LDA(dst, b, h) do { _Pragma("unroll") for (int m = 0; m < 4; ++m) _Pragma("unroll") for (int k = 0; k < 2; ++k) dst[m][k] = *(const LAS bf16x8*)(lds + PG8_SA(b, h) + aoff + m * 2048 + k * 1024); } while (0)
; #define PG8_LDB(dst, b, h) do { _Pragma("unroll") for (int n = 0; n < 2; ++n) _Pragma("unroll") for (int k = 0; k < 2; ++k) dst[n][k] = *(const LAS bf16x8*)(lds + PG8_SB(b, h) + boff + n * 2048 + k * 1024); } while (0)
; #define PG8_MMA(ai, bj, At, Bt) do { __builtin_amdgcn_s_setprio(1); _Pragma("unroll") for (int m = 0; m < 4; ++m) _Pragma("unroll") for (int n = 0; n < 2; ++n) _Pragma("unroll") for (int k = 0; k < 2; ++k) \
;         acc[ai][bj][m][n] = __builtin_amdgcn_mfma_f32_16x16x32_bf16(Bt[n][k], At[m][k], acc[ai][bj][m][n], 0, 0, 0); __builtin_amdgcn_s_setprio(0); } while (0)
; #define PG8_WAIT_V(n) asm volatile("s_waitcnt vmcnt(" #n ")" ::: "memory")
; #define PG8_WAIT_L(n) asm volatile("s_waitcnt lgkmcnt(" #n ")" ::: "memory")
; #define PG8_BAR __builtin_amdgcn_s_barrier()
; #define PG8_SCHED __builtin_amdgcn_sched_barrier(0)
; __device__ __forceinline__ void gemm_phase(LAS unsigned char* lds, const Params& p, const bf16_t* gA, const bf16_t* gBt, const int gM, const int gN, const int gK, const int epi, const int perm, bf16_t* const Hp, const int goff, const float coef) {
;     ...
;         for (int t = 0; t < nt; t += 2) {
;             const bool last = (t == nt - 2);
;             const char* a1 = cA + (size_t)(t + 1) * kstep;
;             const char* a2 = last ? nA : cA + (size_t)(t + 2) * kstep; const char* b2 = last ? nB : cB + (size_t)(t + 2) * kstep;
;             const char* a3 = a2 + kstep; const char* b3 = b2 + kstep;
;             PG8_LDB(B0, 0, 0); PG8_LDB(B1, 0, 1); PG8_SCHED; PG8_LDA(At, 0, 0); PG8_STAGE(PG8_SA(1, 1), a1 + hstep, voffA);
;             PG8_WAIT_V(8); PG8_WAIT_L(0); PG8_BAR; PG8_MMA(0, 0, At, B0); PG8_MMA(0, 1, At, B1); PG8_BAR; PG8_SCHED;
;             PG8_LDA(At, 0, 1); PG8_STAGE(PG8_SB(0, 0), b2, voffB); PG8_STAGE(PG8_SB(0, 1), b2 + hstep, voffB); PG8_STAGE(PG8_SA(0, 0), a2, voffA);
.LBB0_264:
	ds_read_b128 v[146:149], v167
	ds_read_b128 v[150:153], v167 offset:1024
	ds_read_b128 v[154:157], v167 offset:2048
	ds_read_b128 v[170:173], v167 offset:3072
	ds_read_b128 v[174:177], v168
	ds_read_b128 v[178:181], v168 offset:1024
	ds_read_b128 v[182:185], v168 offset:2048
	ds_read_b128 v[186:189], v168 offset:3072
	s_add_i32 s58, s34, 2
	s_add_u32 s35, s30, 0xffea0080
	s_addc_u32 s38, s31, -1
	s_cmp_eq_u32 s55, s34
	s_cselect_b32 s34, s28, s56
	s_cselect_b32 s39, s27, s38
	s_cselect_b32 s38, s26, s35
	s_cselect_b32 s35, s29, s57
	v_lshl_add_u64 v[222:223], s[30:31], 0, v[136:137]
	s_add_i32 m0, s17, 0xc000
	ds_read_b128 v[190:193], v169
	ds_read_b128 v[194:197], v169 offset:1024
	ds_read_b128 v[198:201], v169 offset:2048
	ds_read_b128 v[202:205], v169 offset:3072
	ds_read_b128 v[206:209], v169 offset:4096
	ds_read_b128 v[210:213], v169 offset:5120
	ds_read_b128 v[214:217], v169 offset:6144
	ds_read_b128 v[218:221], v169 offset:7168
	global_load_lds_dwordx4 v[222:223], off
	v_lshl_add_u64 v[222:223], s[30:31], 0, v[138:139]
	s_add_i32 m0, s17, 0xe000
	s_nop 0
	global_load_lds_dwordx4 v[222:223], off
	s_waitcnt vmcnt(8)
	s_waitcnt lgkmcnt(0)
	s_barrier
	s_setprio 1
	s_waitcnt lgkmcnt(0)
	v_mfma_f32_16x16x32_bf16 v[124:127], v[146:149], v[190:193], v[124:127]
	v_mfma_f32_16x16x32_bf16 v[120:123], v[154:157], v[190:193], v[120:123]
	v_mfma_f32_16x16x32_bf16 v[116:119], v[146:149], v[198:201], v[116:119]
	v_mfma_f32_16x16x32_bf16 v[112:115], v[154:157], v[198:201], v[112:115]
	v_mfma_f32_16x16x32_bf16 v[108:111], v[146:149], v[206:209], v[108:111]
	v_mfma_f32_16x16x32_bf16 v[104:107], v[154:157], v[206:209], v[104:107]
	v_mfma_f32_16x16x32_bf16 v[100:103], v[146:149], v[214:217], v[100:103]
	v_mfma_f32_16x16x32_bf16 v[96:99], v[154:157], v[214:217], v[96:99]
	v_mfma_f32_16x16x32_bf16 v[124:127], v[150:153], v[194:197], v[124:127]
	v_mfma_f32_16x16x32_bf16 v[120:123], v[170:173], v[194:197], v[120:123]
	v_mfma_f32_16x16x32_bf16 v[116:119], v[150:153], v[202:205], v[116:119]
	v_mfma_f32_16x16x32_bf16 v[112:115], v[170:173], v[202:205], v[112:115]
	v_mfma_f32_16x16x32_bf16 v[108:111], v[150:153], v[210:213], v[108:111]
	v_mfma_f32_16x16x32_bf16 v[104:107], v[170:173], v[210:213], v[104:107]
	v_mfma_f32_16x16x32_bf16 v[100:103], v[150:153], v[218:221], v[100:103]
	v_mfma_f32_16x16x32_bf16 v[96:99], v[170:173], v[218:221], v[96:99]
	v_mfma_f32_16x16x32_bf16 v[68:71], v[174:177], v[190:193], v[68:71]
	v_mfma_f32_16x16x32_bf16 v[60:63], v[182:185], v[190:193], v[60:63]
	v_mfma_f32_16x16x32_bf16 v[52:55], v[174:177], v[198:201], v[52:55]
	v_mfma_f32_16x16x32_bf16 v[48:51], v[182:185], v[198:201], v[48:51]
	v_mfma_f32_16x16x32_bf16 v[44:47], v[174:177], v[206:209], v[44:47]
	v_mfma_f32_16x16x32_bf16 v[40:43], v[182:185], v[206:209], v[40:43]
	v_mfma_f32_16x16x32_bf16 v[36:39], v[174:177], v[214:217], v[36:39]
	v_mfma_f32_16x16x32_bf16 v[32:35], v[182:185], v[214:217], v[32:35]
	v_mfma_f32_16x16x32_bf16 v[68:71], v[178:181], v[194:197], v[68:71]
	v_mfma_f32_16x16x32_bf16 v[60:63], v[186:189], v[194:197], v[60:63]
	v_mfma_f32_16x16x32_bf16 v[52:55], v[178:181], v[202:205], v[52:55]
	v_mfma_f32_16x16x32_bf16 v[48:51], v[186:189], v[202:205], v[48:51]
	v_mfma_f32_16x16x32_bf16 v[44:47], v[178:181], v[210:213], v[44:47]
	v_mfma_f32_16x16x32_bf16 v[40:43], v[186:189], v[210:213], v[40:43]
	v_mfma_f32_16x16x32_bf16 v[36:39], v[178:181], v[218:221], v[36:39]
	v_mfma_f32_16x16x32_bf16 v[32:35], v[186:189], v[218:221], v[32:35]
	s_setprio 0
	s_barrier
	s_add_i32 s59, s46, s16
	v_lshl_add_u64 v[222:223], s[34:35], 0, v[130:131]
	s_mov_b32 m0, s59
	ds_read_b128 v[190:193], v169 offset:16384
	ds_read_b128 v[194:197], v169 offset:17408
	ds_read_b128 v[198:201], v169 offset:18432
	ds_read_b128 v[202:205], v169 offset:19456
	ds_read_b128 v[206:209], v169 offset:20480
	ds_read_b128 v[210:213], v169 offset:21504
	ds_read_b128 v[214:217], v169 offset:22528
	ds_read_b128 v[218:221], v169 offset:23552
	global_load_lds_dwordx4 v[222:223], off
	s_add_i32 m0, s59, 0x2000
	s_add_u32 s60, s34, 0x160000
	v_lshl_add_u64 v[224:225], s[34:35], 0, v[134:135]
	s_addc_u32 s61, s35, 0
	s_add_i32 s59, s47, s16
	global_load_lds_dwordx4 v[224:225], off
	v_lshl_add_u64 v[226:227], s[60:61], 0, v[130:131]
	s_mov_b32 m0, s59
	v_lshl_add_u64 v[228:229], s[38:39], 0, v[132:133]
	global_load_lds_dwordx4 v[226:227], off
	v_lshl_add_u64 v[226:227], s[60:61], 0, v[134:135]
	s_add_i32 m0, s59, 0x2000
	s_nop 0
	global_load_lds_dwordx4 v[226:227], off
	v_lshl_add_u64 v[226:227], s[38:39], 0, v[128:129]
	s_mov_b32 m0, s17
	s_nop 0
	global_load_lds_dwordx4 v[226:227], off
	s_mov_b32 m0, s18
	s_nop 0
	global_load_lds_dwordx4 v[228:229], off
	s_waitcnt vmcnt(8)
	s_waitcnt lgkmcnt(0)
	s_barrier
; #define PG8_STAGE(bufoff, gbase, voff) do { _Pragma("unroll") for (int _i = 0; _i < 2; ++_i) \
;         __builtin_amdgcn_global_load_lds((const unsigned*)((const char*)(gbase) + (voff)[_i]), (LAS unsigned*)(lds + (bufoff) + ldsw + _i * 8192), 16, 0, 0); } while (0)
; #define PG8_LDA(dst, b, h) do { _Pragma("unroll") for (int m = 0; m < 4; ++m) _Pragma("unroll") for (int k = 0; k < 2; ++k) dst[m][k] = *(const LAS bf16x8*)(lds + PG8_SA(b, h) + aoff + m * 2048 + k * 1024); } while (0)
; #define PG8_LDB(dst, b, h) do { _Pragma("unroll") for (int n = 0; n < 2; ++n) _Pragma("unroll") for (int k = 0; k < 2; ++k) dst[n][k] = *(const LAS bf16x8*)(lds + PG8_SB(b, h) + boff + n * 2048 + k * 1024); } while (0)
; #define PG8_MMA(ai, bj, At, Bt) do { __builtin_amdgcn_s_setprio(1); _Pragma("unroll") for (int m = 0; m < 4; ++m) _Pragma("unroll") for (int n = 0; n < 2; ++n) _Pragma("unroll") for (int k = 0; k < 2; ++k) \
;         acc[ai][bj][m][n] = __builtin_amdgcn_mfma_f32_16x16x32_bf16(Bt[n][k], At[m][k], acc[ai][bj][m][n], 0, 0, 0); __builtin_amdgcn_s_setprio(0); } while (0)
; #define PG8_WAIT_V(n) asm volatile("s_waitcnt vmcnt(" #n ")" ::: "memory")
; #define PG8_WAIT_L(n) asm volatile("s_waitcnt lgkmcnt(" #n ")" ::: "memory")
; #define PG8_BAR __builtin_amdgcn_s_barrier()
; #define PG8_SCHED __builtin_amdgcn_sched_barrier(0)
; __device__ __forceinline__ void gemm_phase(LAS unsigned char* lds, const Params& p, const bf16_t* gA, const bf16_t* gBt, const int gM, const int gN, const int gK, const int epi, const int perm, bf16_t* const Hp, const int goff, const float coef) {
;     ...
;             PG8_WAIT_V(8); PG8_WAIT_L(0); PG8_BAR; PG8_MMA(1, 0, At, B0); PG8_MMA(1, 1, At, B1); PG8_BAR; PG8_SCHED;
;             PG8_LDB(B0, 1, 0); PG8_LDB(B1, 1, 1); PG8_SCHED; PG8_LDA(At, 1, 0); PG8_STAGE(PG8_SA(0, 1), a2 + hstep, voffA);
;             PG8_WAIT_V(8); PG8_WAIT_L(0); PG8_BAR; PG8_MMA(0, 0, At, B0); PG8_MMA(0, 1, At, B1); PG8_BAR; PG8_SCHED;
	s_setprio 1
	s_waitcnt lgkmcnt(0)
	v_mfma_f32_16x16x32_bf16 v[92:95], v[146:149], v[190:193], v[92:95]
	v_mfma_f32_16x16x32_bf16 v[88:91], v[154:157], v[190:193], v[88:91]
	v_mfma_f32_16x16x32_bf16 v[84:87], v[146:149], v[198:201], v[84:87]
	v_mfma_f32_16x16x32_bf16 v[80:83], v[154:157], v[198:201], v[80:83]
	v_mfma_f32_16x16x32_bf16 v[76:79], v[146:149], v[206:209], v[76:79]
	v_mfma_f32_16x16x32_bf16 v[72:75], v[154:157], v[206:209], v[72:75]
	v_mfma_f32_16x16x32_bf16 v[64:67], v[146:149], v[214:217], v[64:67]
	v_mfma_f32_16x16x32_bf16 v[56:59], v[154:157], v[214:217], v[56:59]
	v_mfma_f32_16x16x32_bf16 v[92:95], v[150:153], v[194:197], v[92:95]
	v_mfma_f32_16x16x32_bf16 v[88:91], v[170:173], v[194:197], v[88:91]
	v_mfma_f32_16x16x32_bf16 v[84:87], v[150:153], v[202:205], v[84:87]
	v_mfma_f32_16x16x32_bf16 v[80:83], v[170:173], v[202:205], v[80:83]
	v_mfma_f32_16x16x32_bf16 v[76:79], v[150:153], v[210:213], v[76:79]
	v_mfma_f32_16x16x32_bf16 v[72:75], v[170:173], v[210:213], v[72:75]
	v_mfma_f32_16x16x32_bf16 v[64:67], v[150:153], v[218:221], v[64:67]
	v_mfma_f32_16x16x32_bf16 v[56:59], v[170:173], v[218:221], v[56:59]
	v_mfma_f32_16x16x32_bf16 v[28:31], v[174:177], v[190:193], v[28:31]
	v_mfma_f32_16x16x32_bf16 v[24:27], v[182:185], v[190:193], v[24:27]
	v_mfma_f32_16x16x32_bf16 v[20:23], v[174:177], v[198:201], v[20:23]
	v_mfma_f32_16x16x32_bf16 v[16:19], v[182:185], v[198:201], v[16:19]
	v_mfma_f32_16x16x32_bf16 v[12:15], v[174:177], v[206:209], v[12:15]
	v_mfma_f32_16x16x32_bf16 v[8:11], v[182:185], v[206:209], v[8:11]
	v_mfma_f32_16x16x32_bf16 v[4:7], v[174:177], v[214:217], v[4:7]
	v_mfma_f32_16x16x32_bf16 v[0:3], v[182:185], v[214:217], v[0:3]
	v_mfma_f32_16x16x32_bf16 v[28:31], v[178:181], v[194:197], v[28:31]
	v_mfma_f32_16x16x32_bf16 v[24:27], v[186:189], v[194:197], v[24:27]
	v_mfma_f32_16x16x32_bf16 v[20:23], v[178:181], v[202:205], v[20:23]
	v_mfma_f32_16x16x32_bf16 v[16:19], v[186:189], v[202:205], v[16:19]
	v_mfma_f32_16x16x32_bf16 v[12:15], v[178:181], v[210:213], v[12:15]
	v_mfma_f32_16x16x32_bf16 v[8:11], v[186:189], v[210:213], v[8:11]
	v_mfma_f32_16x16x32_bf16 v[4:7], v[178:181], v[218:221], v[4:7]
	v_mfma_f32_16x16x32_bf16 v[0:3], v[186:189], v[218:221], v[0:3]
	s_setprio 0
	s_barrier
	s_add_i32 s59, 0, 0x18000
	s_add_i32 s60, 0, 0x1c000
	v_add_u32_e32 v170, s59, v158
	v_add_u32_e32 v186, s60, v158
	ds_read_b128 v[146:149], v170
	ds_read_b128 v[150:153], v170 offset:1024
	ds_read_b128 v[154:157], v170 offset:2048
	ds_read_b128 v[170:173], v170 offset:3072
	ds_read_b128 v[174:177], v186
	ds_read_b128 v[178:181], v186 offset:1024
	ds_read_b128 v[182:185], v186 offset:2048
	ds_read_b128 v[186:189], v186 offset:3072
	s_add_u32 s38, s38, 0x160000
	s_addc_u32 s39, s39, 0
	s_mov_b32 m0, s19
	v_lshl_add_u64 v[230:231], s[38:39], 0, v[128:129]
	ds_read_b128 v[190:193], v169 offset:32768
	ds_read_b128 v[194:197], v169 offset:33792
	ds_read_b128 v[198:201], v169 offset:34816
	ds_read_b128 v[202:205], v169 offset:35840
	ds_read_b128 v[206:209], v169 offset:36864
	ds_read_b128 v[210:213], v169 offset:37888
	ds_read_b128 v[214:217], v169 offset:38912
	ds_read_b128 v[218:221], v169 offset:39936
	global_load_lds_dwordx4 v[230:231], off
	v_lshl_add_u64 v[230:231], s[38:39], 0, v[132:133]
	s_mov_b32 m0, s20
	s_nop 0
	global_load_lds_dwordx4 v[230:231], off
	s_waitcnt vmcnt(8)
	s_waitcnt lgkmcnt(0)
	s_barrier
	s_setprio 1
	s_waitcnt lgkmcnt(0)
	v_mfma_f32_16x16x32_bf16 v[124:127], v[146:149], v[190:193], v[124:127]
	v_mfma_f32_16x16x32_bf16 v[120:123], v[154:157], v[190:193], v[120:123]
	v_mfma_f32_16x16x32_bf16 v[116:119], v[146:149], v[198:201], v[116:119]
	v_mfma_f32_16x16x32_bf16 v[112:115], v[154:157], v[198:201], v[112:115]
	v_mfma_f32_16x16x32_bf16 v[108:111], v[146:149], v[206:209], v[108:111]
	v_mfma_f32_16x16x32_bf16 v[104:107], v[154:157], v[206:209], v[104:107]
	v_mfma_f32_16x16x32_bf16 v[100:103], v[146:149], v[214:217], v[100:103]
	v_mfma_f32_16x16x32_bf16 v[96:99], v[154:157], v[214:217], v[96:99]
	v_mfma_f32_16x16x32_bf16 v[124:127], v[150:153], v[194:197], v[124:127]
	v_mfma_f32_16x16x32_bf16 v[120:123], v[170:173], v[194:197], v[120:123]
	v_mfma_f32_16x16x32_bf16 v[116:119], v[150:153], v[202:205], v[116:119]
	v_mfma_f32_16x16x32_bf16 v[112:115], v[170:173], v[202:205], v[112:115]
	v_mfma_f32_16x16x32_bf16 v[108:111], v[150:153], v[210:213], v[108:111]
	v_mfma_f32_16x16x32_bf16 v[104:107], v[170:173], v[210:213], v[104:107]
	v_mfma_f32_16x16x32_bf16 v[100:103], v[150:153], v[218:221], v[100:103]
	v_mfma_f32_16x16x32_bf16 v[96:99], v[170:173], v[218:221], v[96:99]
	v_mfma_f32_16x16x32_bf16 v[68:71], v[174:177], v[190:193], v[68:71]
	v_mfma_f32_16x16x32_bf16 v[60:63], v[182:185], v[190:193], v[60:63]
	v_mfma_f32_16x16x32_bf16 v[52:55], v[174:177], v[198:201], v[52:55]
	v_mfma_f32_16x16x32_bf16 v[48:51], v[182:185], v[198:201], v[48:51]
	v_mfma_f32_16x16x32_bf16 v[44:47], v[174:177], v[206:209], v[44:47]
	v_mfma_f32_16x16x32_bf16 v[40:43], v[182:185], v[206:209], v[40:43]
	v_mfma_f32_16x16x32_bf16 v[36:39], v[174:177], v[214:217], v[36:39]
	v_mfma_f32_16x16x32_bf16 v[32:35], v[182:185], v[214:217], v[32:35]
	v_mfma_f32_16x16x32_bf16 v[68:71], v[178:181], v[194:197], v[68:71]
	v_mfma_f32_16x16x32_bf16 v[60:63], v[186:189], v[194:197], v[60:63]
	v_mfma_f32_16x16x32_bf16 v[52:55], v[178:181], v[202:205], v[52:55]
	v_mfma_f32_16x16x32_bf16 v[48:51], v[186:189], v[202:205], v[48:51]
	v_mfma_f32_16x16x32_bf16 v[44:47], v[178:181], v[210:213], v[44:47]
	v_mfma_f32_16x16x32_bf16 v[40:43], v[186:189], v[210:213], v[40:43]
	v_mfma_f32_16x16x32_bf16 v[36:39], v[178:181], v[218:221], v[36:39]
	v_mfma_f32_16x16x32_bf16 v[32:35], v[186:189], v[218:221], v[32:35]
	s_setprio 0
	s_barrier
; #define PG8_STAGE(bufoff, gbase, voff) do { _Pragma("unroll") for (int _i = 0; _i < 2; ++_i) \
;         __builtin_amdgcn_global_load_lds((const unsigned*)((const char*)(gbase) + (voff)[_i]), (LAS unsigned*)(lds + (bufoff) + ldsw + _i * 8192), 16, 0, 0); } while (0)
; #define PG8_LDA(dst, b, h) do { _Pragma("unroll") for (int m = 0; m < 4; ++m) _Pragma("unroll") for (int k = 0; k < 2; ++k) dst[m][k] = *(const LAS bf16x8*)(lds + PG8_SA(b, h) + aoff + m * 2048 + k * 1024); } while (0)
; #define PG8_MMA(ai, bj, At, Bt) do { __builtin_amdgcn_s_setprio(1); _Pragma("unroll") for (int m = 0; m < 4; ++m) _Pragma("unroll") for (int n = 0; n < 2; ++n) _Pragma("unroll") for (int k = 0; k < 2; ++k) \
;         acc[ai][bj][m][n] = __builtin_amdgcn_mfma_f32_16x16x32_bf16(Bt[n][k], At[m][k], acc[ai][bj][m][n], 0, 0, 0); __builtin_amdgcn_s_setprio(0); } while (0)
; #define PG8_WAIT_V(n) asm volatile("s_waitcnt vmcnt(" #n ")" ::: "memory")
; #define PG8_WAIT_L(n) asm volatile("s_waitcnt lgkmcnt(" #n ")" ::: "memory")
; #define PG8_BAR __builtin_amdgcn_s_barrier()
; #define PG8_SCHED __builtin_amdgcn_sched_barrier(0)
; __device__ __forceinline__ void gemm_phase(LAS unsigned char* lds, const Params& p, const bf16_t* gA, const bf16_t* gBt, const int gM, const int gN, const int gK, const int epi, const int perm, bf16_t* const Hp, const int goff, const float coef) {
;     ...
;             PG8_LDA(At, 1, 1); PG8_STAGE(PG8_SB(1, 0), b3, voffB); PG8_STAGE(PG8_SB(1, 1), b3 + hstep, voffB); PG8_STAGE(PG8_SA(1, 0), a3, voffA);
;             PG8_WAIT_V(8); PG8_WAIT_L(0); PG8_BAR; PG8_MMA(1, 0, At, B0); PG8_MMA(1, 1, At, B1); PG8_BAR; PG8_SCHED;
;         }
;         if (wr == 0) PG8_BAR;
	s_add_i32 s38, s59, s16
	v_lshl_add_u64 v[222:223], v[222:223], 0, s[12:13]
	s_mov_b32 m0, s38
	ds_read_b128 v[190:193], v169 offset:49152
	ds_read_b128 v[194:197], v169 offset:50176
	ds_read_b128 v[198:201], v169 offset:51200
	ds_read_b128 v[202:205], v169 offset:52224
	ds_read_b128 v[206:209], v169 offset:53248
	ds_read_b128 v[210:213], v169 offset:54272
	ds_read_b128 v[214:217], v169 offset:55296
	ds_read_b128 v[218:221], v169 offset:56320
	global_load_lds_dwordx4 v[222:223], off
	s_add_i32 m0, s38, 0x2000
	s_add_u32 s34, s34, 0x160080
	v_lshl_add_u64 v[222:223], v[224:225], 0, s[12:13]
	s_addc_u32 s35, s35, 0
	s_add_i32 s38, s60, s16
	global_load_lds_dwordx4 v[222:223], off
	v_lshl_add_u64 v[222:223], s[34:35], 0, v[130:131]
	s_mov_b32 m0, s38
	s_nop 0
	global_load_lds_dwordx4 v[222:223], off
	v_lshl_add_u64 v[222:223], s[34:35], 0, v[134:135]
	s_add_i32 m0, s38, 0x2000
	s_nop 0
	global_load_lds_dwordx4 v[222:223], off
	v_lshl_add_u64 v[222:223], v[226:227], 0, s[12:13]
	s_mov_b32 m0, s23
	s_nop 0
	global_load_lds_dwordx4 v[222:223], off
	v_lshl_add_u64 v[222:223], v[228:229], 0, s[12:13]
	s_mov_b32 m0, s33
	s_nop 0
	global_load_lds_dwordx4 v[222:223], off
	s_waitcnt vmcnt(8)
	s_waitcnt lgkmcnt(0)
	s_barrier
	s_setprio 1
	s_waitcnt lgkmcnt(0)
	v_mfma_f32_16x16x32_bf16 v[92:95], v[146:149], v[190:193], v[92:95]
	v_mfma_f32_16x16x32_bf16 v[88:91], v[154:157], v[190:193], v[88:91]
	v_mfma_f32_16x16x32_bf16 v[84:87], v[146:149], v[198:201], v[84:87]
	v_mfma_f32_16x16x32_bf16 v[80:83], v[154:157], v[198:201], v[80:83]
	v_mfma_f32_16x16x32_bf16 v[76:79], v[146:149], v[206:209], v[76:79]
	v_mfma_f32_16x16x32_bf16 v[72:75], v[154:157], v[206:209], v[72:75]
	v_mfma_f32_16x16x32_bf16 v[64:67], v[146:149], v[214:217], v[64:67]
	v_mfma_f32_16x16x32_bf16 v[56:59], v[154:157], v[214:217], v[56:59]
	v_mfma_f32_16x16x32_bf16 v[92:95], v[150:153], v[194:197], v[92:95]
	v_mfma_f32_16x16x32_bf16 v[88:91], v[170:173], v[194:197], v[88:91]
	v_mfma_f32_16x16x32_bf16 v[84:87], v[150:153], v[202:205], v[84:87]
	v_mfma_f32_16x16x32_bf16 v[80:83], v[170:173], v[202:205], v[80:83]
	v_mfma_f32_16x16x32_bf16 v[76:79], v[150:153], v[210:213], v[76:79]
	v_mfma_f32_16x16x32_bf16 v[72:75], v[170:173], v[210:213], v[72:75]
	v_mfma_f32_16x16x32_bf16 v[64:67], v[150:153], v[218:221], v[64:67]
	v_mfma_f32_16x16x32_bf16 v[56:59], v[170:173], v[218:221], v[56:59]
	v_mfma_f32_16x16x32_bf16 v[28:31], v[174:177], v[190:193], v[28:31]
	v_mfma_f32_16x16x32_bf16 v[24:27], v[182:185], v[190:193], v[24:27]
	v_mfma_f32_16x16x32_bf16 v[20:23], v[174:177], v[198:201], v[20:23]
	v_mfma_f32_16x16x32_bf16 v[16:19], v[182:185], v[198:201], v[16:19]
	v_mfma_f32_16x16x32_bf16 v[12:15], v[174:177], v[206:209], v[12:15]
	v_mfma_f32_16x16x32_bf16 v[8:11], v[182:185], v[206:209], v[8:11]
	v_mfma_f32_16x16x32_bf16 v[4:7], v[174:177], v[214:217], v[4:7]
	v_mfma_f32_16x16x32_bf16 v[0:3], v[182:185], v[214:217], v[0:3]
	v_mfma_f32_16x16x32_bf16 v[28:31], v[178:181], v[194:197], v[28:31]
	v_mfma_f32_16x16x32_bf16 v[24:27], v[186:189], v[194:197], v[24:27]
	v_mfma_f32_16x16x32_bf16 v[20:23], v[178:181], v[202:205], v[20:23]
	v_mfma_f32_16x16x32_bf16 v[16:19], v[186:189], v[202:205], v[16:19]
	v_mfma_f32_16x16x32_bf16 v[12:15], v[178:181], v[210:213], v[12:15]
	v_mfma_f32_16x16x32_bf16 v[8:11], v[186:189], v[210:213], v[8:11]
	v_mfma_f32_16x16x32_bf16 v[4:7], v[178:181], v[218:221], v[4:7]
	v_mfma_f32_16x16x32_bf16 v[0:3], v[186:189], v[218:221], v[0:3]
	s_setprio 0
	s_barrier
	s_add_u32 s30, s30, 0x100
	s_addc_u32 s31, s31, 0
	s_add_u32 s56, s56, 0x100
	s_addc_u32 s57, s57, 0
	s_cmp_ge_u32 s58, s54
	s_mov_b32 s34, s58
	s_cbranch_scc0 .LBB0_264
	s_and_b64 vcc, exec, s[24:25]
	s_cbranch_vccz .LBB0_267
	s_barrier

; #define PG8_STAGE(bufoff, gbase, voff) do { _Pragma("unroll") for (int _i = 0; _i < 2; ++_i) \
;         __builtin_amdgcn_global_load_lds((const unsigned*)((const char*)(gbase) + (voff)[_i]), (LAS unsigned*)(lds + (bufoff) + ldsw + _i * 8192), 16, 0, 0); } while (0)
; #define PG8_LDA(dst, b, h) do { _Pragma("unroll") for (int m = 0; m < 4; ++m) _Pragma("unroll") for (int k = 0; k < 2; ++k) dst[m][k] = *(const LAS bf16x8*)(lds + PG8_SA(b, h) + aoff + m * 2048 + k * 1024); } while (0)
; #define PG8_LDB(dst, b, h) do { _Pragma("unroll") for (int n = 0; n < 2; ++n) _Pragma("unroll") for (int k = 0; k < 2; ++k) dst[n][k] = *(const LAS bf16x8*)(lds + PG8_SB(b, h) + boff + n * 2048 + k * 1024); } while (0)
; #define PG8_MMA(ai, bj, At, Bt) do { __builtin_amdgcn_s_setprio(1); _Pragma("unroll") for (int m = 0; m < 4; ++m) _Pragma("unroll") for (int n = 0; n < 2; ++n) _Pragma("unroll") for (int k = 0; k < 2; ++k) \
;         acc[ai][bj][m][n] = __builtin_amdgcn_mfma_f32_16x16x32_bf16(Bt[n][k], At[m][k], acc[ai][bj][m][n], 0, 0, 0); __builtin_amdgcn_s_setprio(0); } while (0)
; #define PG8_WAIT_V(n) asm volatile("s_waitcnt vmcnt(" #n ")" ::: "memory")
; #define PG8_WAIT_L(n) asm volatile("s_waitcnt lgkmcnt(" #n ")" ::: "memory")
; #define PG8_BAR __builtin_amdgcn_s_barrier()
; #define PG8_SCHED __builtin_amdgcn_sched_barrier(0)
; __device__ __forceinline__ void gemm_phase(LAS unsigned char* lds, const Params& p, const bf16_t* gA, const bf16_t* gBt, const int gM, const int gN, const int gK, const int epi, const int perm, bf16_t* const Hp, const int goff, const float coef) {
;     ...
;         for (int t = 0; t < nt; t += 2) {
;             const bool last = (t == nt - 2);
;             const char* a1 = cA + (size_t)(t + 1) * kstep;
;             const char* a2 = last ? nA : cA + (size_t)(t + 2) * kstep; const char* b2 = last ? nB : cB + (size_t)(t + 2) * kstep;
;             const char* a3 = a2 + kstep; const char* b3 = b2 + kstep;
;             PG8_LDB(B0, 0, 0); PG8_LDB(B1, 0, 1); PG8_SCHED; PG8_LDA(At, 0, 0); PG8_STAGE(PG8_SA(1, 1), a1 + hstep, voffA);
;             PG8_WAIT_V(8); PG8_WAIT_L(0); PG8_BAR; PG8_MMA(0, 0, At, B0); PG8_MMA(0, 1, At, B1); PG8_BAR; PG8_SCHED;
;             PG8_LDA(At, 0, 1); PG8_STAGE(PG8_SB(0, 0), b2, voffB); PG8_STAGE(PG8_SB(0, 1), b2 + hstep, voffB); PG8_STAGE(PG8_SA(0, 0), a2, voffA);
.LBB0_436:
	ds_read_b128 v[128:131], v180
	ds_read_b128 v[132:135], v180 offset:1024
	ds_read_b128 v[136:139], v180 offset:2048
	ds_read_b128 v[184:187], v180 offset:3072
	ds_read_b128 v[188:191], v181
	ds_read_b128 v[192:195], v181 offset:1024
	ds_read_b128 v[196:199], v181 offset:2048
	ds_read_b128 v[200:203], v181 offset:3072
	s_add_i32 s37, s45, 2
	s_add_u32 s4, s0, 0xfff80080
	s_addc_u32 s5, s1, -1
	s_cmp_eq_u32 s23, s45
	s_cselect_b32 s49, s14, s5
	s_cselect_b32 s48, s15, s4
	s_cselect_b32 s5, s16, s35
	s_cselect_b32 s4, s17, s33
	v_lshl_add_u64 v[168:169], s[0:1], 0, v[160:161]
	s_add_i32 m0, s47, 0xc000
	ds_read_b128 v[204:207], v182
	ds_read_b128 v[208:211], v182 offset:1024
	ds_read_b128 v[212:215], v182 offset:2048
	ds_read_b128 v[216:219], v182 offset:3072
	ds_read_b128 v[220:223], v182 offset:4096
	ds_read_b128 v[224:227], v182 offset:5120
	ds_read_b128 v[228:231], v182 offset:6144
	ds_read_b128 v[232:235], v182 offset:7168
	global_load_lds_dwordx4 v[168:169], off
	v_lshl_add_u64 v[168:169], s[0:1], 0, v[162:163]
	s_add_i32 m0, s47, 0xe000
	s_nop 0
	global_load_lds_dwordx4 v[168:169], off
	s_waitcnt vmcnt(8)
	s_waitcnt lgkmcnt(0)
	s_barrier
	s_setprio 1
	s_waitcnt lgkmcnt(0)
	v_mfma_f32_16x16x32_bf16 v[124:127], v[128:131], v[204:207], v[124:127]
	v_mfma_f32_16x16x32_bf16 v[120:123], v[136:139], v[204:207], v[120:123]
	v_mfma_f32_16x16x32_bf16 v[108:111], v[128:131], v[212:215], v[108:111]
	v_mfma_f32_16x16x32_bf16 v[104:107], v[136:139], v[212:215], v[104:107]
	v_mfma_f32_16x16x32_bf16 v[92:95], v[128:131], v[220:223], v[92:95]
	v_mfma_f32_16x16x32_bf16 v[88:91], v[136:139], v[220:223], v[88:91]
	v_mfma_f32_16x16x32_bf16 v[76:79], v[128:131], v[228:231], v[76:79]
	v_mfma_f32_16x16x32_bf16 v[72:75], v[136:139], v[228:231], v[72:75]
	v_mfma_f32_16x16x32_bf16 v[124:127], v[132:135], v[208:211], v[124:127]
	v_mfma_f32_16x16x32_bf16 v[120:123], v[184:187], v[208:211], v[120:123]
	v_mfma_f32_16x16x32_bf16 v[108:111], v[132:135], v[216:219], v[108:111]
	v_mfma_f32_16x16x32_bf16 v[104:107], v[184:187], v[216:219], v[104:107]
	v_mfma_f32_16x16x32_bf16 v[92:95], v[132:135], v[224:227], v[92:95]
	v_mfma_f32_16x16x32_bf16 v[88:91], v[184:187], v[224:227], v[88:91]
	v_mfma_f32_16x16x32_bf16 v[76:79], v[132:135], v[232:235], v[76:79]
	v_mfma_f32_16x16x32_bf16 v[72:75], v[184:187], v[232:235], v[72:75]
	v_mfma_f32_16x16x32_bf16 v[116:119], v[188:191], v[204:207], v[116:119]
	v_mfma_f32_16x16x32_bf16 v[112:115], v[196:199], v[204:207], v[112:115]
	v_mfma_f32_16x16x32_bf16 v[100:103], v[188:191], v[212:215], v[100:103]
	v_mfma_f32_16x16x32_bf16 v[96:99], v[196:199], v[212:215], v[96:99]
	v_mfma_f32_16x16x32_bf16 v[84:87], v[188:191], v[220:223], v[84:87]
	v_mfma_f32_16x16x32_bf16 v[80:83], v[196:199], v[220:223], v[80:83]
	v_mfma_f32_16x16x32_bf16 v[68:71], v[188:191], v[228:231], v[68:71]
	v_mfma_f32_16x16x32_bf16 v[64:67], v[196:199], v[228:231], v[64:67]
	v_mfma_f32_16x16x32_bf16 v[116:119], v[192:195], v[208:211], v[116:119]
	v_mfma_f32_16x16x32_bf16 v[112:115], v[200:203], v[208:211], v[112:115]
	v_mfma_f32_16x16x32_bf16 v[100:103], v[192:195], v[216:219], v[100:103]
	v_mfma_f32_16x16x32_bf16 v[96:99], v[200:203], v[216:219], v[96:99]
	v_mfma_f32_16x16x32_bf16 v[84:87], v[192:195], v[224:227], v[84:87]
	v_mfma_f32_16x16x32_bf16 v[80:83], v[200:203], v[224:227], v[80:83]
	v_mfma_f32_16x16x32_bf16 v[68:71], v[192:195], v[232:235], v[68:71]
	v_mfma_f32_16x16x32_bf16 v[64:67], v[200:203], v[232:235], v[64:67]
	s_setprio 0
	s_barrier
	s_add_i32 s45, s19, s52
	v_lshl_add_u64 v[168:169], s[4:5], 0, v[144:145]
	s_mov_b32 m0, s45
	ds_read_b128 v[204:207], v182 offset:16384
	ds_read_b128 v[208:211], v182 offset:17408
	ds_read_b128 v[212:215], v182 offset:18432
	ds_read_b128 v[216:219], v182 offset:19456
	ds_read_b128 v[220:223], v182 offset:20480
	ds_read_b128 v[224:227], v182 offset:21504
	ds_read_b128 v[228:231], v182 offset:22528
	ds_read_b128 v[232:235], v182 offset:23552
	global_load_lds_dwordx4 v[168:169], off
	s_add_i32 m0, s45, 0x2000
	s_add_u32 s50, s4, 0x80000
	v_lshl_add_u64 v[236:237], s[4:5], 0, v[148:149]
	s_addc_u32 s51, s5, 0
	s_add_i32 s45, s21, s52
	global_load_lds_dwordx4 v[236:237], off
	v_lshl_add_u64 v[238:239], s[50:51], 0, v[144:145]
	s_mov_b32 m0, s45
	v_lshl_add_u64 v[240:241], s[48:49], 0, v[146:147]
	global_load_lds_dwordx4 v[238:239], off
	v_lshl_add_u64 v[238:239], s[50:51], 0, v[148:149]
	s_add_i32 m0, s45, 0x2000
	s_nop 0
	global_load_lds_dwordx4 v[238:239], off
	v_lshl_add_u64 v[238:239], s[48:49], 0, v[142:143]
	s_mov_b32 m0, s47
	s_nop 0
	global_load_lds_dwordx4 v[238:239], off
	s_mov_b32 m0, s53
	s_nop 0
	global_load_lds_dwordx4 v[240:241], off
	s_waitcnt vmcnt(8)
	s_waitcnt lgkmcnt(0)
	s_barrier
; #define PG8_STAGE(bufoff, gbase, voff) do { _Pragma("unroll") for (int _i = 0; _i < 2; ++_i) \
;         __builtin_amdgcn_global_load_lds((const unsigned*)((const char*)(gbase) + (voff)[_i]), (LAS unsigned*)(lds + (bufoff) + ldsw + _i * 8192), 16, 0, 0); } while (0)
; #define PG8_LDA(dst, b, h) do { _Pragma("unroll") for (int m = 0; m < 4; ++m) _Pragma("unroll") for (int k = 0; k < 2; ++k) dst[m][k] = *(const LAS bf16x8*)(lds + PG8_SA(b, h) + aoff + m * 2048 + k * 1024); } while (0)
; #define PG8_LDB(dst, b, h) do { _Pragma("unroll") for (int n = 0; n < 2; ++n) _Pragma("unroll") for (int k = 0; k < 2; ++k) dst[n][k] = *(const LAS bf16x8*)(lds + PG8_SB(b, h) + boff + n * 2048 + k * 1024); } while (0)
; #define PG8_MMA(ai, bj, At, Bt) do { __builtin_amdgcn_s_setprio(1); _Pragma("unroll") for (int m = 0; m < 4; ++m) _Pragma("unroll") for (int n = 0; n < 2; ++n) _Pragma("unroll") for (int k = 0; k < 2; ++k) \
;         acc[ai][bj][m][n] = __builtin_amdgcn_mfma_f32_16x16x32_bf16(Bt[n][k], At[m][k], acc[ai][bj][m][n], 0, 0, 0); __builtin_amdgcn_s_setprio(0); } while (0)
; #define PG8_WAIT_V(n) asm volatile("s_waitcnt vmcnt(" #n ")" ::: "memory")
; #define PG8_WAIT_L(n) asm volatile("s_waitcnt lgkmcnt(" #n ")" ::: "memory")
; #define PG8_BAR __builtin_amdgcn_s_barrier()
; #define PG8_SCHED __builtin_amdgcn_sched_barrier(0)
; __device__ __forceinline__ void gemm_phase(LAS unsigned char* lds, const Params& p, const bf16_t* gA, const bf16_t* gBt, const int gM, const int gN, const int gK, const int epi, const int perm, bf16_t* const Hp, const int goff, const float coef) {
;     ...
;             PG8_WAIT_V(8); PG8_WAIT_L(0); PG8_BAR; PG8_MMA(1, 0, At, B0); PG8_MMA(1, 1, At, B1); PG8_BAR; PG8_SCHED;
;             PG8_LDB(B0, 1, 0); PG8_LDB(B1, 1, 1); PG8_SCHED; PG8_LDA(At, 1, 0); PG8_STAGE(PG8_SA(0, 1), a2 + hstep, voffA);
;             PG8_WAIT_V(8); PG8_WAIT_L(0); PG8_BAR; PG8_MMA(0, 0, At, B0); PG8_MMA(0, 1, At, B1); PG8_BAR; PG8_SCHED;
	s_setprio 1
	s_waitcnt lgkmcnt(0)
	v_mfma_f32_16x16x32_bf16 v[60:63], v[128:131], v[204:207], v[60:63]
	v_mfma_f32_16x16x32_bf16 v[56:59], v[136:139], v[204:207], v[56:59]
	v_mfma_f32_16x16x32_bf16 v[44:47], v[128:131], v[212:215], v[44:47]
	v_mfma_f32_16x16x32_bf16 v[40:43], v[136:139], v[212:215], v[40:43]
	v_mfma_f32_16x16x32_bf16 v[28:31], v[128:131], v[220:223], v[28:31]
	v_mfma_f32_16x16x32_bf16 v[24:27], v[136:139], v[220:223], v[24:27]
	v_mfma_f32_16x16x32_bf16 v[12:15], v[128:131], v[228:231], v[12:15]
	v_mfma_f32_16x16x32_bf16 v[8:11], v[136:139], v[228:231], v[8:11]
	v_mfma_f32_16x16x32_bf16 v[60:63], v[132:135], v[208:211], v[60:63]
	v_mfma_f32_16x16x32_bf16 v[56:59], v[184:187], v[208:211], v[56:59]
	v_mfma_f32_16x16x32_bf16 v[44:47], v[132:135], v[216:219], v[44:47]
	v_mfma_f32_16x16x32_bf16 v[40:43], v[184:187], v[216:219], v[40:43]
	v_mfma_f32_16x16x32_bf16 v[28:31], v[132:135], v[224:227], v[28:31]
	v_mfma_f32_16x16x32_bf16 v[24:27], v[184:187], v[224:227], v[24:27]
	v_mfma_f32_16x16x32_bf16 v[12:15], v[132:135], v[232:235], v[12:15]
	v_mfma_f32_16x16x32_bf16 v[8:11], v[184:187], v[232:235], v[8:11]
	v_mfma_f32_16x16x32_bf16 v[52:55], v[188:191], v[204:207], v[52:55]
	v_mfma_f32_16x16x32_bf16 v[48:51], v[196:199], v[204:207], v[48:51]
	v_mfma_f32_16x16x32_bf16 v[36:39], v[188:191], v[212:215], v[36:39]
	v_mfma_f32_16x16x32_bf16 v[32:35], v[196:199], v[212:215], v[32:35]
	v_mfma_f32_16x16x32_bf16 v[20:23], v[188:191], v[220:223], v[20:23]
	v_mfma_f32_16x16x32_bf16 v[16:19], v[196:199], v[220:223], v[16:19]
	v_mfma_f32_16x16x32_bf16 v[4:7], v[188:191], v[228:231], v[4:7]
	v_mfma_f32_16x16x32_bf16 v[0:3], v[196:199], v[228:231], v[0:3]
	v_mfma_f32_16x16x32_bf16 v[52:55], v[192:195], v[208:211], v[52:55]
	v_mfma_f32_16x16x32_bf16 v[48:51], v[200:203], v[208:211], v[48:51]
	v_mfma_f32_16x16x32_bf16 v[36:39], v[192:195], v[216:219], v[36:39]
	v_mfma_f32_16x16x32_bf16 v[32:35], v[200:203], v[216:219], v[32:35]
	v_mfma_f32_16x16x32_bf16 v[20:23], v[192:195], v[224:227], v[20:23]
	v_mfma_f32_16x16x32_bf16 v[16:19], v[200:203], v[224:227], v[16:19]
	v_mfma_f32_16x16x32_bf16 v[4:7], v[192:195], v[232:235], v[4:7]
	v_mfma_f32_16x16x32_bf16 v[0:3], v[200:203], v[232:235], v[0:3]
	s_setprio 0
	s_barrier
	s_add_i32 s45, 0, 0x18000
	v_add_u32_e32 v150, s45, v171
	s_add_i32 s50, 0, 0x1c000
	ds_read_b128 v[128:131], v150
	ds_read_b128 v[132:135], v150 offset:1024
	ds_read_b128 v[136:139], v150 offset:2048
	ds_read_b128 v[184:187], v150 offset:3072
	v_add_u32_e32 v150, s50, v171
	ds_read_b128 v[188:191], v150
	ds_read_b128 v[192:195], v150 offset:1024
	ds_read_b128 v[196:199], v150 offset:2048
	ds_read_b128 v[200:203], v150 offset:3072
	s_add_u32 s48, s48, 0x80000
	s_addc_u32 s49, s49, 0
	s_mov_b32 m0, s54
	v_lshl_add_u64 v[242:243], s[48:49], 0, v[142:143]
	ds_read_b128 v[204:207], v182 offset:32768
	ds_read_b128 v[208:211], v182 offset:33792
	ds_read_b128 v[212:215], v182 offset:34816
	ds_read_b128 v[216:219], v182 offset:35840
	ds_read_b128 v[220:223], v182 offset:36864
	ds_read_b128 v[224:227], v182 offset:37888
	ds_read_b128 v[228:231], v182 offset:38912
	ds_read_b128 v[232:235], v182 offset:39936
	global_load_lds_dwordx4 v[242:243], off
	v_lshl_add_u64 v[242:243], s[48:49], 0, v[146:147]
	s_mov_b32 m0, s55
	s_nop 0
	global_load_lds_dwordx4 v[242:243], off
	s_waitcnt vmcnt(8)
	s_waitcnt lgkmcnt(0)
	s_barrier
	s_setprio 1
	s_waitcnt lgkmcnt(0)
	v_mfma_f32_16x16x32_bf16 v[124:127], v[128:131], v[204:207], v[124:127]
	v_mfma_f32_16x16x32_bf16 v[120:123], v[136:139], v[204:207], v[120:123]
	v_mfma_f32_16x16x32_bf16 v[108:111], v[128:131], v[212:215], v[108:111]
	v_mfma_f32_16x16x32_bf16 v[104:107], v[136:139], v[212:215], v[104:107]
	v_mfma_f32_16x16x32_bf16 v[92:95], v[128:131], v[220:223], v[92:95]
	v_mfma_f32_16x16x32_bf16 v[88:91], v[136:139], v[220:223], v[88:91]
	v_mfma_f32_16x16x32_bf16 v[76:79], v[128:131], v[228:231], v[76:79]
	v_mfma_f32_16x16x32_bf16 v[72:75], v[136:139], v[228:231], v[72:75]
	v_mfma_f32_16x16x32_bf16 v[124:127], v[132:135], v[208:211], v[124:127]
	v_mfma_f32_16x16x32_bf16 v[120:123], v[184:187], v[208:211], v[120:123]
	v_mfma_f32_16x16x32_bf16 v[108:111], v[132:135], v[216:219], v[108:111]
	v_mfma_f32_16x16x32_bf16 v[104:107], v[184:187], v[216:219], v[104:107]
	v_mfma_f32_16x16x32_bf16 v[92:95], v[132:135], v[224:227], v[92:95]
	v_mfma_f32_16x16x32_bf16 v[88:91], v[184:187], v[224:227], v[88:91]
	v_mfma_f32_16x16x32_bf16 v[76:79], v[132:135], v[232:235], v[76:79]
	v_mfma_f32_16x16x32_bf16 v[72:75], v[184:187], v[232:235], v[72:75]
	v_mfma_f32_16x16x32_bf16 v[116:119], v[188:191], v[204:207], v[116:119]
	v_mfma_f32_16x16x32_bf16 v[112:115], v[196:199], v[204:207], v[112:115]
	v_mfma_f32_16x16x32_bf16 v[100:103], v[188:191], v[212:215], v[100:103]
	v_mfma_f32_16x16x32_bf16 v[96:99], v[196:199], v[212:215], v[96:99]
	v_mfma_f32_16x16x32_bf16 v[84:87], v[188:191], v[220:223], v[84:87]
	v_mfma_f32_16x16x32_bf16 v[80:83], v[196:199], v[220:223], v[80:83]
	v_mfma_f32_16x16x32_bf16 v[68:71], v[188:191], v[228:231], v[68:71]
	v_mfma_f32_16x16x32_bf16 v[64:67], v[196:199], v[228:231], v[64:67]
	v_mfma_f32_16x16x32_bf16 v[116:119], v[192:195], v[208:211], v[116:119]
	v_mfma_f32_16x16x32_bf16 v[112:115], v[200:203], v[208:211], v[112:115]
	v_mfma_f32_16x16x32_bf16 v[100:103], v[192:195], v[216:219], v[100:103]
	v_mfma_f32_16x16x32_bf16 v[96:99], v[200:203], v[216:219], v[96:99]
	v_mfma_f32_16x16x32_bf16 v[84:87], v[192:195], v[224:227], v[84:87]
	v_mfma_f32_16x16x32_bf16 v[80:83], v[200:203], v[224:227], v[80:83]
	v_mfma_f32_16x16x32_bf16 v[68:71], v[192:195], v[232:235], v[68:71]
	v_mfma_f32_16x16x32_bf16 v[64:67], v[200:203], v[232:235], v[64:67]
	s_setprio 0
	s_barrier
; #define PG8_STAGE(bufoff, gbase, voff) do { _Pragma("unroll") for (int _i = 0; _i < 2; ++_i) \
;         __builtin_amdgcn_global_load_lds((const unsigned*)((const char*)(gbase) + (voff)[_i]), (LAS unsigned*)(lds + (bufoff) + ldsw + _i * 8192), 16, 0, 0); } while (0)
; #define PG8_LDA(dst, b, h) do { _Pragma("unroll") for (int m = 0; m < 4; ++m) _Pragma("unroll") for (int k = 0; k < 2; ++k) dst[m][k] = *(const LAS bf16x8*)(lds + PG8_SA(b, h) + aoff + m * 2048 + k * 1024); } while (0)
; #define PG8_MMA(ai, bj, At, Bt) do { __builtin_amdgcn_s_setprio(1); _Pragma("unroll") for (int m = 0; m < 4; ++m) _Pragma("unroll") for (int n = 0; n < 2; ++n) _Pragma("unroll") for (int k = 0; k < 2; ++k) \
;         acc[ai][bj][m][n] = __builtin_amdgcn_mfma_f32_16x16x32_bf16(Bt[n][k], At[m][k], acc[ai][bj][m][n], 0, 0, 0); __builtin_amdgcn_s_setprio(0); } while (0)
; #define PG8_WAIT_V(n) asm volatile("s_waitcnt vmcnt(" #n ")" ::: "memory")
; #define PG8_WAIT_L(n) asm volatile("s_waitcnt lgkmcnt(" #n ")" ::: "memory")
; #define PG8_BAR __builtin_amdgcn_s_barrier()
; #define PG8_SCHED __builtin_amdgcn_sched_barrier(0)
; __device__ __forceinline__ void gemm_epilogue(const Params& p, const int epi, bf16_t* const Hp, const int goff, const float coef, const f32x4 (&acc)[2][2][4][2], const pg8::Unit& u, int wr, int wc, int fr, int fq) {
;     ...
;         const int seg = u.pn >> 2;
;         const bool lat = u.pm < 128;
;         if (seg < 5) {
; __device__ __forceinline__ void gemm_phase(LAS unsigned char* lds, const Params& p, const bf16_t* gA, const bf16_t* gBt, const int gM, const int gN, const int gK, const int epi, const int perm, bf16_t* const Hp, const int goff, const float coef) {
;     ...
;             PG8_LDA(At, 1, 1); PG8_STAGE(PG8_SB(1, 0), b3, voffB); PG8_STAGE(PG8_SB(1, 1), b3 + hstep, voffB); PG8_STAGE(PG8_SA(1, 0), a3, voffA);
;             PG8_WAIT_V(8); PG8_WAIT_L(0); PG8_BAR; PG8_MMA(1, 0, At, B0); PG8_MMA(1, 1, At, B1); PG8_BAR; PG8_SCHED;
;         }
;         if (wr == 0) PG8_BAR;
	s_add_i32 s45, s45, s52
	v_lshl_add_u64 v[168:169], v[168:169], 0, s[10:11]
	s_mov_b32 m0, s45
	ds_read_b128 v[204:207], v182 offset:49152
	ds_read_b128 v[208:211], v182 offset:50176
	ds_read_b128 v[212:215], v182 offset:51200
	ds_read_b128 v[216:219], v182 offset:52224
	ds_read_b128 v[220:223], v182 offset:53248
	ds_read_b128 v[224:227], v182 offset:54272
	ds_read_b128 v[228:231], v182 offset:55296
	ds_read_b128 v[232:235], v182 offset:56320
	global_load_lds_dwordx4 v[168:169], off
	s_add_i32 m0, s45, 0x2000
	s_add_u32 s4, s4, 0x80080
	v_lshl_add_u64 v[168:169], v[236:237], 0, s[10:11]
	s_addc_u32 s5, s5, 0
	s_add_i32 s45, s50, s52
	global_load_lds_dwordx4 v[168:169], off
	v_lshl_add_u64 v[168:169], s[4:5], 0, v[144:145]
	s_mov_b32 m0, s45
	s_nop 0
	global_load_lds_dwordx4 v[168:169], off
	v_lshl_add_u64 v[168:169], s[4:5], 0, v[148:149]
	s_add_i32 m0, s45, 0x2000
	s_nop 0
	global_load_lds_dwordx4 v[168:169], off
	v_lshl_add_u64 v[168:169], v[238:239], 0, s[10:11]
	s_mov_b32 m0, s57
	s_nop 0
	global_load_lds_dwordx4 v[168:169], off
	v_lshl_add_u64 v[168:169], v[240:241], 0, s[10:11]
	s_mov_b32 m0, s58
	s_nop 0
	global_load_lds_dwordx4 v[168:169], off
	s_waitcnt vmcnt(8)
	s_waitcnt lgkmcnt(0)
	s_barrier
	s_setprio 1
	s_waitcnt lgkmcnt(0)
	v_mfma_f32_16x16x32_bf16 v[60:63], v[128:131], v[204:207], v[60:63]
	v_mfma_f32_16x16x32_bf16 v[56:59], v[136:139], v[204:207], v[56:59]
	v_mfma_f32_16x16x32_bf16 v[44:47], v[128:131], v[212:215], v[44:47]
	v_mfma_f32_16x16x32_bf16 v[40:43], v[136:139], v[212:215], v[40:43]
	v_mfma_f32_16x16x32_bf16 v[28:31], v[128:131], v[220:223], v[28:31]
	v_mfma_f32_16x16x32_bf16 v[24:27], v[136:139], v[220:223], v[24:27]
	v_mfma_f32_16x16x32_bf16 v[12:15], v[128:131], v[228:231], v[12:15]
	v_mfma_f32_16x16x32_bf16 v[8:11], v[136:139], v[228:231], v[8:11]
	v_mfma_f32_16x16x32_bf16 v[60:63], v[132:135], v[208:211], v[60:63]
	v_mfma_f32_16x16x32_bf16 v[56:59], v[184:187], v[208:211], v[56:59]
	v_mfma_f32_16x16x32_bf16 v[44:47], v[132:135], v[216:219], v[44:47]
	v_mfma_f32_16x16x32_bf16 v[40:43], v[184:187], v[216:219], v[40:43]
	v_mfma_f32_16x16x32_bf16 v[28:31], v[132:135], v[224:227], v[28:31]
	v_mfma_f32_16x16x32_bf16 v[24:27], v[184:187], v[224:227], v[24:27]
	v_mfma_f32_16x16x32_bf16 v[12:15], v[132:135], v[232:235], v[12:15]
	v_mfma_f32_16x16x32_bf16 v[8:11], v[184:187], v[232:235], v[8:11]
	v_mfma_f32_16x16x32_bf16 v[52:55], v[188:191], v[204:207], v[52:55]
	v_mfma_f32_16x16x32_bf16 v[48:51], v[196:199], v[204:207], v[48:51]
	v_mfma_f32_16x16x32_bf16 v[36:39], v[188:191], v[212:215], v[36:39]
	v_mfma_f32_16x16x32_bf16 v[32:35], v[196:199], v[212:215], v[32:35]
	v_mfma_f32_16x16x32_bf16 v[20:23], v[188:191], v[220:223], v[20:23]
	v_mfma_f32_16x16x32_bf16 v[16:19], v[196:199], v[220:223], v[16:19]
	v_mfma_f32_16x16x32_bf16 v[4:7], v[188:191], v[228:231], v[4:7]
	v_mfma_f32_16x16x32_bf16 v[0:3], v[196:199], v[228:231], v[0:3]
	v_mfma_f32_16x16x32_bf16 v[52:55], v[192:195], v[208:211], v[52:55]
	v_mfma_f32_16x16x32_bf16 v[48:51], v[200:203], v[208:211], v[48:51]
	v_mfma_f32_16x16x32_bf16 v[36:39], v[192:195], v[216:219], v[36:39]
	v_mfma_f32_16x16x32_bf16 v[32:35], v[200:203], v[216:219], v[32:35]
	v_mfma_f32_16x16x32_bf16 v[20:23], v[192:195], v[224:227], v[20:23]
	v_mfma_f32_16x16x32_bf16 v[16:19], v[200:203], v[224:227], v[16:19]
	v_mfma_f32_16x16x32_bf16 v[4:7], v[192:195], v[232:235], v[4:7]
	v_mfma_f32_16x16x32_bf16 v[0:3], v[200:203], v[232:235], v[0:3]
	s_setprio 0
	s_barrier
	s_add_u32 s0, s0, 0x100
	s_addc_u32 s1, s1, 0
	s_add_u32 s33, s33, 0x100
	s_addc_u32 s35, s35, 0
	s_cmp_ge_u32 s37, s22
	s_mov_b32 s45, s37
	s_cbranch_scc0 .LBB0_436
	s_and_b64 vcc, exec, s[12:13]
	s_cbranch_vccnz .LBB0_440
	s_ashr_i32 s14, s46, 2
	s_cmp_gt_i32 s14, 4
	s_mov_b64 s[0:1], -1
	s_cbranch_scc1 .LBB0_441

; #define PG8_STAGE(bufoff, gbase, voff) do { _Pragma("unroll") for (int _i = 0; _i < 2; ++_i) \
;         __builtin_amdgcn_global_load_lds((const unsigned*)((const char*)(gbase) + (voff)[_i]), (LAS unsigned*)(lds + (bufoff) + ldsw + _i * 8192), 16, 0, 0); } while (0)
; #define PG8_LDA(dst, b, h) do { _Pragma("unroll") for (int m = 0; m < 4; ++m) _Pragma("unroll") for (int k = 0; k < 2; ++k) dst[m][k] = *(const LAS bf16x8*)(lds + PG8_SA(b, h) + aoff + m * 2048 + k * 1024); } while (0)
; #define PG8_LDB(dst, b, h) do { _Pragma("unroll") for (int n = 0; n < 2; ++n) _Pragma("unroll") for (int k = 0; k < 2; ++k) dst[n][k] = *(const LAS bf16x8*)(lds + PG8_SB(b, h) + boff + n * 2048 + k * 1024); } while (0)
; #define PG8_MMA(ai, bj, At, Bt) do { __builtin_amdgcn_s_setprio(1); _Pragma("unroll") for (int m = 0; m < 4; ++m) _Pragma("unroll") for (int n = 0; n < 2; ++n) _Pragma("unroll") for (int k = 0; k < 2; ++k) \
;         acc[ai][bj][m][n] = __builtin_amdgcn_mfma_f32_16x16x32_bf16(Bt[n][k], At[m][k], acc[ai][bj][m][n], 0, 0, 0); __builtin_amdgcn_s_setprio(0); } while (0)
; #define PG8_WAIT_V(n) asm volatile("s_waitcnt vmcnt(" #n ")" ::: "memory")
; #define PG8_WAIT_L(n) asm volatile("s_waitcnt lgkmcnt(" #n ")" ::: "memory")
; #define PG8_BAR __builtin_amdgcn_s_barrier()
; #define PG8_SCHED __builtin_amdgcn_sched_barrier(0)
; __device__ __forceinline__ void gemm_phase(LAS unsigned char* lds, const Params& p, const bf16_t* gA, const bf16_t* gBt, const int gM, const int gN, const int gK, const int epi, const int perm, bf16_t* const Hp, const int goff, const float coef) {
;     ...
;         for (int t = 0; t < nt; t += 2) {
;             const bool last = (t == nt - 2);
;             const char* a1 = cA + (size_t)(t + 1) * kstep;
;             const char* a2 = last ? nA : cA + (size_t)(t + 2) * kstep; const char* b2 = last ? nB : cB + (size_t)(t + 2) * kstep;
;             const char* a3 = a2 + kstep; const char* b3 = b2 + kstep;
;             PG8_LDB(B0, 0, 0); PG8_LDB(B1, 0, 1); PG8_SCHED; PG8_LDA(At, 0, 0); PG8_STAGE(PG8_SA(1, 1), a1 + hstep, voffA);
;             PG8_WAIT_V(8); PG8_WAIT_L(0); PG8_BAR; PG8_MMA(0, 0, At, B0); PG8_MMA(0, 1, At, B1); PG8_BAR; PG8_SCHED;
;             PG8_LDA(At, 0, 1); PG8_STAGE(PG8_SB(0, 0), b2, voffB); PG8_STAGE(PG8_SB(0, 1), b2 + hstep, voffB); PG8_STAGE(PG8_SA(0, 0), a2, voffA);
.LBB0_1593:
	ds_read_b128 v[128:131], v174
	ds_read_b128 v[132:135], v174 offset:1024
	ds_read_b128 v[152:155], v174 offset:2048
	ds_read_b128 v[156:159], v174 offset:3072
	ds_read_b128 v[160:163], v175
	ds_read_b128 v[178:181], v175 offset:1024
	ds_read_b128 v[182:185], v175 offset:2048
	ds_read_b128 v[186:189], v175 offset:3072
	s_add_i32 s56, s30, 2
	s_add_u32 s28, s26, 0xfff80080
	s_addc_u32 s29, s27, -1
	s_cmp_eq_u32 s53, s30
	s_cselect_b32 s30, s19, s28
	s_cselect_b32 s31, s13, s29
	s_cselect_b32 s29, s15, s55
	s_cselect_b32 s28, s25, s54
	v_lshl_add_u64 v[222:223], s[26:27], 0, v[146:147]
	s_add_i32 m0, s37, 0xc000
	ds_read_b128 v[190:193], v176
	ds_read_b128 v[194:197], v176 offset:1024
	ds_read_b128 v[198:201], v176 offset:2048
	ds_read_b128 v[202:205], v176 offset:3072
	ds_read_b128 v[206:209], v176 offset:4096
	ds_read_b128 v[210:213], v176 offset:5120
	ds_read_b128 v[214:217], v176 offset:6144
	ds_read_b128 v[218:221], v176 offset:7168
	global_load_lds_dwordx4 v[222:223], off
	v_lshl_add_u64 v[222:223], s[26:27], 0, v[148:149]
	s_add_i32 m0, s37, 0xe000
	s_nop 0
	global_load_lds_dwordx4 v[222:223], off
	s_waitcnt vmcnt(8)
	s_waitcnt lgkmcnt(0)
	s_barrier
	s_setprio 1
	s_waitcnt lgkmcnt(0)
	v_mfma_f32_16x16x32_bf16 v[124:127], v[128:131], v[190:193], v[124:127]
	v_mfma_f32_16x16x32_bf16 v[120:123], v[152:155], v[190:193], v[120:123]
	v_mfma_f32_16x16x32_bf16 v[116:119], v[128:131], v[198:201], v[116:119]
	v_mfma_f32_16x16x32_bf16 v[112:115], v[152:155], v[198:201], v[112:115]
	v_mfma_f32_16x16x32_bf16 v[108:111], v[128:131], v[206:209], v[108:111]
	v_mfma_f32_16x16x32_bf16 v[104:107], v[152:155], v[206:209], v[104:107]
	v_mfma_f32_16x16x32_bf16 v[100:103], v[128:131], v[214:217], v[100:103]
	v_mfma_f32_16x16x32_bf16 v[96:99], v[152:155], v[214:217], v[96:99]
	v_mfma_f32_16x16x32_bf16 v[124:127], v[132:135], v[194:197], v[124:127]
	v_mfma_f32_16x16x32_bf16 v[120:123], v[156:159], v[194:197], v[120:123]
	v_mfma_f32_16x16x32_bf16 v[116:119], v[132:135], v[202:205], v[116:119]
	v_mfma_f32_16x16x32_bf16 v[112:115], v[156:159], v[202:205], v[112:115]
	v_mfma_f32_16x16x32_bf16 v[108:111], v[132:135], v[210:213], v[108:111]
	v_mfma_f32_16x16x32_bf16 v[104:107], v[156:159], v[210:213], v[104:107]
	v_mfma_f32_16x16x32_bf16 v[100:103], v[132:135], v[218:221], v[100:103]
	v_mfma_f32_16x16x32_bf16 v[96:99], v[156:159], v[218:221], v[96:99]
	v_mfma_f32_16x16x32_bf16 v[68:71], v[160:163], v[190:193], v[68:71]
	v_mfma_f32_16x16x32_bf16 v[64:67], v[182:185], v[190:193], v[64:67]
	v_mfma_f32_16x16x32_bf16 v[52:55], v[160:163], v[198:201], v[52:55]
	v_mfma_f32_16x16x32_bf16 v[48:51], v[182:185], v[198:201], v[48:51]
	v_mfma_f32_16x16x32_bf16 v[44:47], v[160:163], v[206:209], v[44:47]
	v_mfma_f32_16x16x32_bf16 v[40:43], v[182:185], v[206:209], v[40:43]
	v_mfma_f32_16x16x32_bf16 v[36:39], v[160:163], v[214:217], v[36:39]
	v_mfma_f32_16x16x32_bf16 v[32:35], v[182:185], v[214:217], v[32:35]
	v_mfma_f32_16x16x32_bf16 v[68:71], v[178:181], v[194:197], v[68:71]
	v_mfma_f32_16x16x32_bf16 v[64:67], v[186:189], v[194:197], v[64:67]
	v_mfma_f32_16x16x32_bf16 v[52:55], v[178:181], v[202:205], v[52:55]
	v_mfma_f32_16x16x32_bf16 v[48:51], v[186:189], v[202:205], v[48:51]
	v_mfma_f32_16x16x32_bf16 v[44:47], v[178:181], v[210:213], v[44:47]
	v_mfma_f32_16x16x32_bf16 v[40:43], v[186:189], v[210:213], v[40:43]
	v_mfma_f32_16x16x32_bf16 v[36:39], v[178:181], v[218:221], v[36:39]
	v_mfma_f32_16x16x32_bf16 v[32:35], v[186:189], v[218:221], v[32:35]
	s_setprio 0
	s_barrier
	s_add_i32 s57, s48, s36
	v_lshl_add_u64 v[222:223], s[28:29], 0, v[138:139]
	s_mov_b32 m0, s57
	ds_read_b128 v[190:193], v176 offset:16384
	ds_read_b128 v[194:197], v176 offset:17408
	ds_read_b128 v[198:201], v176 offset:18432
	ds_read_b128 v[202:205], v176 offset:19456
	ds_read_b128 v[206:209], v176 offset:20480
	ds_read_b128 v[210:213], v176 offset:21504
	ds_read_b128 v[214:217], v176 offset:22528
	ds_read_b128 v[218:221], v176 offset:23552
	global_load_lds_dwordx4 v[222:223], off
	s_add_i32 m0, s57, 0x2000
	s_add_u32 s58, s28, 0x80000
	v_lshl_add_u64 v[224:225], s[28:29], 0, v[144:145]
	s_addc_u32 s59, s29, 0
	s_add_i32 s57, s49, s36
	global_load_lds_dwordx4 v[224:225], off
	v_lshl_add_u64 v[226:227], s[58:59], 0, v[138:139]
	s_mov_b32 m0, s57
	v_lshl_add_u64 v[228:229], s[30:31], 0, v[142:143]
	global_load_lds_dwordx4 v[226:227], off
	v_lshl_add_u64 v[226:227], s[58:59], 0, v[144:145]
	s_add_i32 m0, s57, 0x2000
	s_nop 0
	global_load_lds_dwordx4 v[226:227], off
	v_lshl_add_u64 v[226:227], s[30:31], 0, v[136:137]
	s_mov_b32 m0, s37
	s_nop 0
	global_load_lds_dwordx4 v[226:227], off
	s_mov_b32 m0, s38
	s_nop 0
	global_load_lds_dwordx4 v[228:229], off
	s_waitcnt vmcnt(8)
	s_waitcnt lgkmcnt(0)
	s_barrier
; #define PG8_STAGE(bufoff, gbase, voff) do { _Pragma("unroll") for (int _i = 0; _i < 2; ++_i) \
;         __builtin_amdgcn_global_load_lds((const unsigned*)((const char*)(gbase) + (voff)[_i]), (LAS unsigned*)(lds + (bufoff) + ldsw + _i * 8192), 16, 0, 0); } while (0)
; #define PG8_LDA(dst, b, h) do { _Pragma("unroll") for (int m = 0; m < 4; ++m) _Pragma("unroll") for (int k = 0; k < 2; ++k) dst[m][k] = *(const LAS bf16x8*)(lds + PG8_SA(b, h) + aoff + m * 2048 + k * 1024); } while (0)
; #define PG8_LDB(dst, b, h) do { _Pragma("unroll") for (int n = 0; n < 2; ++n) _Pragma("unroll") for (int k = 0; k < 2; ++k) dst[n][k] = *(const LAS bf16x8*)(lds + PG8_SB(b, h) + boff + n * 2048 + k * 1024); } while (0)
; #define PG8_MMA(ai, bj, At, Bt) do { __builtin_amdgcn_s_setprio(1); _Pragma("unroll") for (int m = 0; m < 4; ++m) _Pragma("unroll") for (int n = 0; n < 2; ++n) _Pragma("unroll") for (int k = 0; k < 2; ++k) \
;         acc[ai][bj][m][n] = __builtin_amdgcn_mfma_f32_16x16x32_bf16(Bt[n][k], At[m][k], acc[ai][bj][m][n], 0, 0, 0); __builtin_amdgcn_s_setprio(0); } while (0)
; #define PG8_WAIT_V(n) asm volatile("s_waitcnt vmcnt(" #n ")" ::: "memory")
; #define PG8_WAIT_L(n) asm volatile("s_waitcnt lgkmcnt(" #n ")" ::: "memory")
; #define PG8_BAR __builtin_amdgcn_s_barrier()
; #define PG8_SCHED __builtin_amdgcn_sched_barrier(0)
; __device__ __forceinline__ void gemm_phase(LAS unsigned char* lds, const Params& p, const bf16_t* gA, const bf16_t* gBt, const int gM, const int gN, const int gK, const int epi, const int perm, bf16_t* const Hp, const int goff, const float coef) {
;     ...
;             PG8_WAIT_V(8); PG8_WAIT_L(0); PG8_BAR; PG8_MMA(1, 0, At, B0); PG8_MMA(1, 1, At, B1); PG8_BAR; PG8_SCHED;
;             PG8_LDB(B0, 1, 0); PG8_LDB(B1, 1, 1); PG8_SCHED; PG8_LDA(At, 1, 0); PG8_STAGE(PG8_SA(0, 1), a2 + hstep, voffA);
;             PG8_WAIT_V(8); PG8_WAIT_L(0); PG8_BAR; PG8_MMA(0, 0, At, B0); PG8_MMA(0, 1, At, B1); PG8_BAR; PG8_SCHED;
	s_setprio 1
	s_waitcnt lgkmcnt(0)
	v_mfma_f32_16x16x32_bf16 v[92:95], v[128:131], v[190:193], v[92:95]
	v_mfma_f32_16x16x32_bf16 v[88:91], v[152:155], v[190:193], v[88:91]
	v_mfma_f32_16x16x32_bf16 v[84:87], v[128:131], v[198:201], v[84:87]
	v_mfma_f32_16x16x32_bf16 v[80:83], v[152:155], v[198:201], v[80:83]
	v_mfma_f32_16x16x32_bf16 v[76:79], v[128:131], v[206:209], v[76:79]
	v_mfma_f32_16x16x32_bf16 v[72:75], v[152:155], v[206:209], v[72:75]
	v_mfma_f32_16x16x32_bf16 v[60:63], v[128:131], v[214:217], v[60:63]
	v_mfma_f32_16x16x32_bf16 v[56:59], v[152:155], v[214:217], v[56:59]
	v_mfma_f32_16x16x32_bf16 v[92:95], v[132:135], v[194:197], v[92:95]
	v_mfma_f32_16x16x32_bf16 v[88:91], v[156:159], v[194:197], v[88:91]
	v_mfma_f32_16x16x32_bf16 v[84:87], v[132:135], v[202:205], v[84:87]
	v_mfma_f32_16x16x32_bf16 v[80:83], v[156:159], v[202:205], v[80:83]
	v_mfma_f32_16x16x32_bf16 v[76:79], v[132:135], v[210:213], v[76:79]
	v_mfma_f32_16x16x32_bf16 v[72:75], v[156:159], v[210:213], v[72:75]
	v_mfma_f32_16x16x32_bf16 v[60:63], v[132:135], v[218:221], v[60:63]
	v_mfma_f32_16x16x32_bf16 v[56:59], v[156:159], v[218:221], v[56:59]
	v_mfma_f32_16x16x32_bf16 v[28:31], v[160:163], v[190:193], v[28:31]
	v_mfma_f32_16x16x32_bf16 v[24:27], v[182:185], v[190:193], v[24:27]
	v_mfma_f32_16x16x32_bf16 v[20:23], v[160:163], v[198:201], v[20:23]
	v_mfma_f32_16x16x32_bf16 v[16:19], v[182:185], v[198:201], v[16:19]
	v_mfma_f32_16x16x32_bf16 v[12:15], v[160:163], v[206:209], v[12:15]
	v_mfma_f32_16x16x32_bf16 v[8:11], v[182:185], v[206:209], v[8:11]
	v_mfma_f32_16x16x32_bf16 v[4:7], v[160:163], v[214:217], v[4:7]
	v_mfma_f32_16x16x32_bf16 v[0:3], v[182:185], v[214:217], v[0:3]
	v_mfma_f32_16x16x32_bf16 v[28:31], v[178:181], v[194:197], v[28:31]
	v_mfma_f32_16x16x32_bf16 v[24:27], v[186:189], v[194:197], v[24:27]
	v_mfma_f32_16x16x32_bf16 v[20:23], v[178:181], v[202:205], v[20:23]
	v_mfma_f32_16x16x32_bf16 v[16:19], v[186:189], v[202:205], v[16:19]
	v_mfma_f32_16x16x32_bf16 v[12:15], v[178:181], v[210:213], v[12:15]
	v_mfma_f32_16x16x32_bf16 v[8:11], v[186:189], v[210:213], v[8:11]
	v_mfma_f32_16x16x32_bf16 v[4:7], v[178:181], v[218:221], v[4:7]
	v_mfma_f32_16x16x32_bf16 v[0:3], v[186:189], v[218:221], v[0:3]
	s_setprio 0
	s_barrier
	s_add_i32 s57, 0, 0x18000
	v_add_u32_e32 v141, s57, v165
	s_add_i32 s58, 0, 0x1c000
	ds_read_b128 v[128:131], v141
	ds_read_b128 v[132:135], v141 offset:1024
	ds_read_b128 v[152:155], v141 offset:2048
	ds_read_b128 v[156:159], v141 offset:3072
	v_add_u32_e32 v141, s58, v165
	ds_read_b128 v[160:163], v141
	ds_read_b128 v[178:181], v141 offset:1024
	ds_read_b128 v[182:185], v141 offset:2048
	ds_read_b128 v[186:189], v141 offset:3072
	s_add_u32 s30, s30, 0x80000
	s_addc_u32 s31, s31, 0
	s_mov_b32 m0, s39
	v_lshl_add_u64 v[230:231], s[30:31], 0, v[136:137]
	ds_read_b128 v[190:193], v176 offset:32768
	ds_read_b128 v[194:197], v176 offset:33792
	ds_read_b128 v[198:201], v176 offset:34816
	ds_read_b128 v[202:205], v176 offset:35840
	ds_read_b128 v[206:209], v176 offset:36864
	ds_read_b128 v[210:213], v176 offset:37888
	ds_read_b128 v[214:217], v176 offset:38912
	ds_read_b128 v[218:221], v176 offset:39936
	global_load_lds_dwordx4 v[230:231], off
	v_lshl_add_u64 v[230:231], s[30:31], 0, v[142:143]
	s_mov_b32 m0, s40
	s_nop 0
	global_load_lds_dwordx4 v[230:231], off
	s_waitcnt vmcnt(8)
	s_waitcnt lgkmcnt(0)
	s_barrier
	s_setprio 1
	s_waitcnt lgkmcnt(0)
	v_mfma_f32_16x16x32_bf16 v[124:127], v[128:131], v[190:193], v[124:127]
	v_mfma_f32_16x16x32_bf16 v[120:123], v[152:155], v[190:193], v[120:123]
	v_mfma_f32_16x16x32_bf16 v[116:119], v[128:131], v[198:201], v[116:119]
	v_mfma_f32_16x16x32_bf16 v[112:115], v[152:155], v[198:201], v[112:115]
	v_mfma_f32_16x16x32_bf16 v[108:111], v[128:131], v[206:209], v[108:111]
	v_mfma_f32_16x16x32_bf16 v[104:107], v[152:155], v[206:209], v[104:107]
	v_mfma_f32_16x16x32_bf16 v[100:103], v[128:131], v[214:217], v[100:103]
	v_mfma_f32_16x16x32_bf16 v[96:99], v[152:155], v[214:217], v[96:99]
	v_mfma_f32_16x16x32_bf16 v[124:127], v[132:135], v[194:197], v[124:127]
	v_mfma_f32_16x16x32_bf16 v[120:123], v[156:159], v[194:197], v[120:123]
	v_mfma_f32_16x16x32_bf16 v[116:119], v[132:135], v[202:205], v[116:119]
	v_mfma_f32_16x16x32_bf16 v[112:115], v[156:159], v[202:205], v[112:115]
	v_mfma_f32_16x16x32_bf16 v[108:111], v[132:135], v[210:213], v[108:111]
	v_mfma_f32_16x16x32_bf16 v[104:107], v[156:159], v[210:213], v[104:107]
	v_mfma_f32_16x16x32_bf16 v[100:103], v[132:135], v[218:221], v[100:103]
	v_mfma_f32_16x16x32_bf16 v[96:99], v[156:159], v[218:221], v[96:99]
	v_mfma_f32_16x16x32_bf16 v[68:71], v[160:163], v[190:193], v[68:71]
	v_mfma_f32_16x16x32_bf16 v[64:67], v[182:185], v[190:193], v[64:67]
	v_mfma_f32_16x16x32_bf16 v[52:55], v[160:163], v[198:201], v[52:55]
	v_mfma_f32_16x16x32_bf16 v[48:51], v[182:185], v[198:201], v[48:51]
	v_mfma_f32_16x16x32_bf16 v[44:47], v[160:163], v[206:209], v[44:47]
	v_mfma_f32_16x16x32_bf16 v[40:43], v[182:185], v[206:209], v[40:43]
	v_mfma_f32_16x16x32_bf16 v[36:39], v[160:163], v[214:217], v[36:39]
	v_mfma_f32_16x16x32_bf16 v[32:35], v[182:185], v[214:217], v[32:35]
	v_mfma_f32_16x16x32_bf16 v[68:71], v[178:181], v[194:197], v[68:71]
	v_mfma_f32_16x16x32_bf16 v[64:67], v[186:189], v[194:197], v[64:67]
	v_mfma_f32_16x16x32_bf16 v[52:55], v[178:181], v[202:205], v[52:55]
	v_mfma_f32_16x16x32_bf16 v[48:51], v[186:189], v[202:205], v[48:51]
	v_mfma_f32_16x16x32_bf16 v[44:47], v[178:181], v[210:213], v[44:47]
	v_mfma_f32_16x16x32_bf16 v[40:43], v[186:189], v[210:213], v[40:43]
	v_mfma_f32_16x16x32_bf16 v[36:39], v[178:181], v[218:221], v[36:39]
	v_mfma_f32_16x16x32_bf16 v[32:35], v[186:189], v[218:221], v[32:35]
	s_setprio 0
	s_barrier
; #define PG8_STAGE(bufoff, gbase, voff) do { _Pragma("unroll") for (int _i = 0; _i < 2; ++_i) \
;         __builtin_amdgcn_global_load_lds((const unsigned*)((const char*)(gbase) + (voff)[_i]), (LAS unsigned*)(lds + (bufoff) + ldsw + _i * 8192), 16, 0, 0); } while (0)
; #define PG8_LDA(dst, b, h) do { _Pragma("unroll") for (int m = 0; m < 4; ++m) _Pragma("unroll") for (int k = 0; k < 2; ++k) dst[m][k] = *(const LAS bf16x8*)(lds + PG8_SA(b, h) + aoff + m * 2048 + k * 1024); } while (0)
; #define PG8_MMA(ai, bj, At, Bt) do { __builtin_amdgcn_s_setprio(1); _Pragma("unroll") for (int m = 0; m < 4; ++m) _Pragma("unroll") for (int n = 0; n < 2; ++n) _Pragma("unroll") for (int k = 0; k < 2; ++k) \
;         acc[ai][bj][m][n] = __builtin_amdgcn_mfma_f32_16x16x32_bf16(Bt[n][k], At[m][k], acc[ai][bj][m][n], 0, 0, 0); __builtin_amdgcn_s_setprio(0); } while (0)
; #define PG8_WAIT_V(n) asm volatile("s_waitcnt vmcnt(" #n ")" ::: "memory")
; #define PG8_WAIT_L(n) asm volatile("s_waitcnt lgkmcnt(" #n ")" ::: "memory")
; #define PG8_BAR __builtin_amdgcn_s_barrier()
; #define PG8_SCHED __builtin_amdgcn_sched_barrier(0)
; __device__ __forceinline__ void gemm_phase(LAS unsigned char* lds, const Params& p, const bf16_t* gA, const bf16_t* gBt, const int gM, const int gN, const int gK, const int epi, const int perm, bf16_t* const Hp, const int goff, const float coef) {
;     ...
;             PG8_LDA(At, 1, 1); PG8_STAGE(PG8_SB(1, 0), b3, voffB); PG8_STAGE(PG8_SB(1, 1), b3 + hstep, voffB); PG8_STAGE(PG8_SA(1, 0), a3, voffA);
;             PG8_WAIT_V(8); PG8_WAIT_L(0); PG8_BAR; PG8_MMA(1, 0, At, B0); PG8_MMA(1, 1, At, B1); PG8_BAR; PG8_SCHED;
;         }
;         if (wr == 0) PG8_BAR;
	s_add_i32 s30, s57, s36
	v_lshl_add_u64 v[222:223], v[222:223], 0, s[8:9]
	s_mov_b32 m0, s30
	ds_read_b128 v[190:193], v176 offset:49152
	ds_read_b128 v[194:197], v176 offset:50176
	ds_read_b128 v[198:201], v176 offset:51200
	ds_read_b128 v[202:205], v176 offset:52224
	ds_read_b128 v[206:209], v176 offset:53248
	ds_read_b128 v[210:213], v176 offset:54272
	ds_read_b128 v[214:217], v176 offset:55296
	ds_read_b128 v[218:221], v176 offset:56320
	global_load_lds_dwordx4 v[222:223], off
	s_add_i32 m0, s30, 0x2000
	s_add_u32 s28, s28, 0x80080
	v_lshl_add_u64 v[222:223], v[224:225], 0, s[8:9]
	s_addc_u32 s29, s29, 0
	s_add_i32 s30, s58, s36
	global_load_lds_dwordx4 v[222:223], off
	v_lshl_add_u64 v[222:223], s[28:29], 0, v[138:139]
	s_mov_b32 m0, s30
	s_nop 0
	global_load_lds_dwordx4 v[222:223], off
	v_lshl_add_u64 v[222:223], s[28:29], 0, v[144:145]
	s_add_i32 m0, s30, 0x2000
	s_nop 0
	global_load_lds_dwordx4 v[222:223], off
	v_lshl_add_u64 v[222:223], v[226:227], 0, s[8:9]
	s_mov_b32 m0, s44
	s_nop 0
	global_load_lds_dwordx4 v[222:223], off
	v_lshl_add_u64 v[222:223], v[228:229], 0, s[8:9]
	s_mov_b32 m0, s45
	s_nop 0
	global_load_lds_dwordx4 v[222:223], off
	s_waitcnt vmcnt(8)
	s_waitcnt lgkmcnt(0)
	s_barrier
	s_setprio 1
	s_waitcnt lgkmcnt(0)
	v_mfma_f32_16x16x32_bf16 v[92:95], v[128:131], v[190:193], v[92:95]
	v_mfma_f32_16x16x32_bf16 v[88:91], v[152:155], v[190:193], v[88:91]
	v_mfma_f32_16x16x32_bf16 v[84:87], v[128:131], v[198:201], v[84:87]
	v_mfma_f32_16x16x32_bf16 v[80:83], v[152:155], v[198:201], v[80:83]
	v_mfma_f32_16x16x32_bf16 v[76:79], v[128:131], v[206:209], v[76:79]
	v_mfma_f32_16x16x32_bf16 v[72:75], v[152:155], v[206:209], v[72:75]
	v_mfma_f32_16x16x32_bf16 v[60:63], v[128:131], v[214:217], v[60:63]
	v_mfma_f32_16x16x32_bf16 v[56:59], v[152:155], v[214:217], v[56:59]
	v_mfma_f32_16x16x32_bf16 v[92:95], v[132:135], v[194:197], v[92:95]
	v_mfma_f32_16x16x32_bf16 v[88:91], v[156:159], v[194:197], v[88:91]
	v_mfma_f32_16x16x32_bf16 v[84:87], v[132:135], v[202:205], v[84:87]
	v_mfma_f32_16x16x32_bf16 v[80:83], v[156:159], v[202:205], v[80:83]
	v_mfma_f32_16x16x32_bf16 v[76:79], v[132:135], v[210:213], v[76:79]
	v_mfma_f32_16x16x32_bf16 v[72:75], v[156:159], v[210:213], v[72:75]
	v_mfma_f32_16x16x32_bf16 v[60:63], v[132:135], v[218:221], v[60:63]
	v_mfma_f32_16x16x32_bf16 v[56:59], v[156:159], v[218:221], v[56:59]
	v_mfma_f32_16x16x32_bf16 v[28:31], v[160:163], v[190:193], v[28:31]
	v_mfma_f32_16x16x32_bf16 v[24:27], v[182:185], v[190:193], v[24:27]
	v_mfma_f32_16x16x32_bf16 v[20:23], v[160:163], v[198:201], v[20:23]
	v_mfma_f32_16x16x32_bf16 v[16:19], v[182:185], v[198:201], v[16:19]
	v_mfma_f32_16x16x32_bf16 v[12:15], v[160:163], v[206:209], v[12:15]
	v_mfma_f32_16x16x32_bf16 v[8:11], v[182:185], v[206:209], v[8:11]
	v_mfma_f32_16x16x32_bf16 v[4:7], v[160:163], v[214:217], v[4:7]
	v_mfma_f32_16x16x32_bf16 v[0:3], v[182:185], v[214:217], v[0:3]
	v_mfma_f32_16x16x32_bf16 v[28:31], v[178:181], v[194:197], v[28:31]
	v_mfma_f32_16x16x32_bf16 v[24:27], v[186:189], v[194:197], v[24:27]
	v_mfma_f32_16x16x32_bf16 v[20:23], v[178:181], v[202:205], v[20:23]
	v_mfma_f32_16x16x32_bf16 v[16:19], v[186:189], v[202:205], v[16:19]
	v_mfma_f32_16x16x32_bf16 v[12:15], v[178:181], v[210:213], v[12:15]
	v_mfma_f32_16x16x32_bf16 v[8:11], v[186:189], v[210:213], v[8:11]
	v_mfma_f32_16x16x32_bf16 v[4:7], v[178:181], v[218:221], v[4:7]
	v_mfma_f32_16x16x32_bf16 v[0:3], v[186:189], v[218:221], v[0:3]
	s_setprio 0
	s_barrier
	s_add_u32 s26, s26, 0x100
	s_addc_u32 s27, s27, 0
	s_add_u32 s54, s54, 0x100
	s_addc_u32 s55, s55, 0
	s_cmp_ge_u32 s56, s52
	s_mov_b32 s30, s56
	s_cbranch_scc0 .LBB0_1593
	s_and_b64 vcc, exec, s[10:11]
	s_cbranch_vccz .LBB0_1596
	s_barrier

; #define PG8_STAGE(bufoff, gbase, voff) do { _Pragma("unroll") for (int _i = 0; _i < 2; ++_i) \
;         __builtin_amdgcn_global_load_lds((const unsigned*)((const char*)(gbase) + (voff)[_i]), (LAS unsigned*)(lds + (bufoff) + ldsw + _i * 8192), 16, 0, 0); } while (0)
; #define PG8_LDA(dst, b, h) do { _Pragma("unroll") for (int m = 0; m < 4; ++m) _Pragma("unroll") for (int k = 0; k < 2; ++k) dst[m][k] = *(const LAS bf16x8*)(lds + PG8_SA(b, h) + aoff + m * 2048 + k * 1024); } while (0)
; #define PG8_LDB(dst, b, h) do { _Pragma("unroll") for (int n = 0; n < 2; ++n) _Pragma("unroll") for (int k = 0; k < 2; ++k) dst[n][k] = *(const LAS bf16x8*)(lds + PG8_SB(b, h) + boff + n * 2048 + k * 1024); } while (0)
; #define PG8_MMA(ai, bj, At, Bt) do { __builtin_amdgcn_s_setprio(1); _Pragma("unroll") for (int m = 0; m < 4; ++m) _Pragma("unroll") for (int n = 0; n < 2; ++n) _Pragma("unroll") for (int k = 0; k < 2; ++k) \
;         acc[ai][bj][m][n] = __builtin_amdgcn_mfma_f32_16x16x32_bf16(Bt[n][k], At[m][k], acc[ai][bj][m][n], 0, 0, 0); __builtin_amdgcn_s_setprio(0); } while (0)
; #define PG8_WAIT_V(n) asm volatile("s_waitcnt vmcnt(" #n ")" ::: "memory")
; #define PG8_WAIT_L(n) asm volatile("s_waitcnt lgkmcnt(" #n ")" ::: "memory")
; #define PG8_BAR __builtin_amdgcn_s_barrier()
; #define PG8_SCHED __builtin_amdgcn_sched_barrier(0)
; __device__ __forceinline__ void gemm_phase(LAS unsigned char* lds, const Params& p, const bf16_t* gA, const bf16_t* gBt, const int gM, const int gN, const int gK, const int epi, const int perm, bf16_t* const Hp, const int goff, const float coef) {
;     ...
;         for (int t = 0; t < nt; t += 2) {
;             const bool last = (t == nt - 2);
;             const char* a1 = cA + (size_t)(t + 1) * kstep;
;             const char* a2 = last ? nA : cA + (size_t)(t + 2) * kstep; const char* b2 = last ? nB : cB + (size_t)(t + 2) * kstep;
;             const char* a3 = a2 + kstep; const char* b3 = b2 + kstep;
;             PG8_LDB(B0, 0, 0); PG8_LDB(B1, 0, 1); PG8_SCHED; PG8_LDA(At, 0, 0); PG8_STAGE(PG8_SA(1, 1), a1 + hstep, voffA);
;             PG8_WAIT_V(8); PG8_WAIT_L(0); PG8_BAR; PG8_MMA(0, 0, At, B0); PG8_MMA(0, 1, At, B1); PG8_BAR; PG8_SCHED;
;             PG8_LDA(At, 0, 1); PG8_STAGE(PG8_SB(0, 0), b2, voffB); PG8_STAGE(PG8_SB(0, 1), b2 + hstep, voffB); PG8_STAGE(PG8_SA(0, 0), a2, voffA);
.LBB0_1737:
	ds_read_b128 v[160:163], v156
	ds_read_b128 v[164:167], v156 offset:1024
	ds_read_b128 v[168:171], v156 offset:2048
	ds_read_b128 v[172:175], v156 offset:3072
	ds_read_b128 v[176:179], v157
	ds_read_b128 v[180:183], v157 offset:1024
	ds_read_b128 v[184:187], v157 offset:2048
	ds_read_b128 v[188:191], v157 offset:3072
	s_add_i32 s54, s30, 2
	s_add_u32 s28, s26, 0xfff80080
	s_addc_u32 s29, s27, -1
	s_cmp_eq_u32 s51, s30
	s_cselect_b32 s30, s48, s28
	s_cselect_b32 s31, s13, s29
	s_cselect_b32 s29, s15, s53
	s_cselect_b32 s28, s49, s52
	v_lshl_add_u64 v[144:145], s[26:27], 0, v[136:137]
	s_add_i32 m0, s23, 0xc000
	ds_read_b128 v[192:195], v158
	ds_read_b128 v[196:199], v158 offset:1024
	ds_read_b128 v[200:203], v158 offset:2048
	ds_read_b128 v[204:207], v158 offset:3072
	ds_read_b128 v[208:211], v158 offset:4096
	ds_read_b128 v[212:215], v158 offset:5120
	ds_read_b128 v[216:219], v158 offset:6144
	ds_read_b128 v[220:223], v158 offset:7168
	global_load_lds_dwordx4 v[144:145], off
	v_lshl_add_u64 v[144:145], s[26:27], 0, v[138:139]
	s_add_i32 m0, s23, 0xe000
	s_nop 0
	global_load_lds_dwordx4 v[144:145], off
	s_waitcnt vmcnt(8)
	s_waitcnt lgkmcnt(0)
	s_barrier
	s_setprio 1
	s_waitcnt lgkmcnt(0)
	v_mfma_f32_16x16x32_bf16 v[124:127], v[160:163], v[192:195], v[124:127]
	v_mfma_f32_16x16x32_bf16 v[120:123], v[168:171], v[192:195], v[120:123]
	v_mfma_f32_16x16x32_bf16 v[108:111], v[160:163], v[200:203], v[108:111]
	v_mfma_f32_16x16x32_bf16 v[104:107], v[168:171], v[200:203], v[104:107]
	v_mfma_f32_16x16x32_bf16 v[92:95], v[160:163], v[208:211], v[92:95]
	v_mfma_f32_16x16x32_bf16 v[88:91], v[168:171], v[208:211], v[88:91]
	v_mfma_f32_16x16x32_bf16 v[76:79], v[160:163], v[216:219], v[76:79]
	v_mfma_f32_16x16x32_bf16 v[72:75], v[168:171], v[216:219], v[72:75]
	v_mfma_f32_16x16x32_bf16 v[124:127], v[164:167], v[196:199], v[124:127]
	v_mfma_f32_16x16x32_bf16 v[120:123], v[172:175], v[196:199], v[120:123]
	v_mfma_f32_16x16x32_bf16 v[108:111], v[164:167], v[204:207], v[108:111]
	v_mfma_f32_16x16x32_bf16 v[104:107], v[172:175], v[204:207], v[104:107]
	v_mfma_f32_16x16x32_bf16 v[92:95], v[164:167], v[212:215], v[92:95]
	v_mfma_f32_16x16x32_bf16 v[88:91], v[172:175], v[212:215], v[88:91]
	v_mfma_f32_16x16x32_bf16 v[76:79], v[164:167], v[220:223], v[76:79]
	v_mfma_f32_16x16x32_bf16 v[72:75], v[172:175], v[220:223], v[72:75]
	v_mfma_f32_16x16x32_bf16 v[116:119], v[176:179], v[192:195], v[116:119]
	v_mfma_f32_16x16x32_bf16 v[112:115], v[184:187], v[192:195], v[112:115]
	v_mfma_f32_16x16x32_bf16 v[100:103], v[176:179], v[200:203], v[100:103]
	v_mfma_f32_16x16x32_bf16 v[96:99], v[184:187], v[200:203], v[96:99]
	v_mfma_f32_16x16x32_bf16 v[84:87], v[176:179], v[208:211], v[84:87]
	v_mfma_f32_16x16x32_bf16 v[80:83], v[184:187], v[208:211], v[80:83]
	v_mfma_f32_16x16x32_bf16 v[68:71], v[176:179], v[216:219], v[68:71]
	v_mfma_f32_16x16x32_bf16 v[64:67], v[184:187], v[216:219], v[64:67]
	v_mfma_f32_16x16x32_bf16 v[116:119], v[180:183], v[196:199], v[116:119]
	v_mfma_f32_16x16x32_bf16 v[112:115], v[188:191], v[196:199], v[112:115]
	v_mfma_f32_16x16x32_bf16 v[100:103], v[180:183], v[204:207], v[100:103]
	v_mfma_f32_16x16x32_bf16 v[96:99], v[188:191], v[204:207], v[96:99]
	v_mfma_f32_16x16x32_bf16 v[84:87], v[180:183], v[212:215], v[84:87]
	v_mfma_f32_16x16x32_bf16 v[80:83], v[188:191], v[212:215], v[80:83]
	v_mfma_f32_16x16x32_bf16 v[68:71], v[180:183], v[220:223], v[68:71]
	v_mfma_f32_16x16x32_bf16 v[64:67], v[188:191], v[220:223], v[64:67]
	s_setprio 0
	s_barrier
	s_add_i32 s55, s44, s36
	v_lshl_add_u64 v[144:145], s[28:29], 0, v[130:131]
	s_mov_b32 m0, s55
	ds_read_b128 v[192:195], v158 offset:16384
	ds_read_b128 v[196:199], v158 offset:17408
	ds_read_b128 v[200:203], v158 offset:18432
	ds_read_b128 v[204:207], v158 offset:19456
	ds_read_b128 v[208:211], v158 offset:20480
	ds_read_b128 v[212:215], v158 offset:21504
	ds_read_b128 v[216:219], v158 offset:22528
	ds_read_b128 v[220:223], v158 offset:23552
	global_load_lds_dwordx4 v[144:145], off
	s_add_i32 m0, s55, 0x2000
	s_add_u32 s56, s28, 0x80000
	v_lshl_add_u64 v[224:225], s[28:29], 0, v[134:135]
	s_addc_u32 s57, s29, 0
	s_add_i32 s55, s45, s36
	global_load_lds_dwordx4 v[224:225], off
	v_lshl_add_u64 v[226:227], s[56:57], 0, v[130:131]
	s_mov_b32 m0, s55
	v_lshl_add_u64 v[228:229], s[30:31], 0, v[132:133]
	global_load_lds_dwordx4 v[226:227], off
	v_lshl_add_u64 v[226:227], s[56:57], 0, v[134:135]
	s_add_i32 m0, s55, 0x2000
	s_nop 0
	global_load_lds_dwordx4 v[226:227], off
	v_lshl_add_u64 v[226:227], s[30:31], 0, v[128:129]
	s_mov_b32 m0, s23
	s_nop 0
	global_load_lds_dwordx4 v[226:227], off
	s_mov_b32 m0, s25
	s_nop 0
	global_load_lds_dwordx4 v[228:229], off
	s_waitcnt vmcnt(8)
	s_waitcnt lgkmcnt(0)
	s_barrier
; #define PG8_STAGE(bufoff, gbase, voff) do { _Pragma("unroll") for (int _i = 0; _i < 2; ++_i) \
;         __builtin_amdgcn_global_load_lds((const unsigned*)((const char*)(gbase) + (voff)[_i]), (LAS unsigned*)(lds + (bufoff) + ldsw + _i * 8192), 16, 0, 0); } while (0)
; #define PG8_LDA(dst, b, h) do { _Pragma("unroll") for (int m = 0; m < 4; ++m) _Pragma("unroll") for (int k = 0; k < 2; ++k) dst[m][k] = *(const LAS bf16x8*)(lds + PG8_SA(b, h) + aoff + m * 2048 + k * 1024); } while (0)
; #define PG8_LDB(dst, b, h) do { _Pragma("unroll") for (int n = 0; n < 2; ++n) _Pragma("unroll") for (int k = 0; k < 2; ++k) dst[n][k] = *(const LAS bf16x8*)(lds + PG8_SB(b, h) + boff + n * 2048 + k * 1024); } while (0)
; #define PG8_MMA(ai, bj, At, Bt) do { __builtin_amdgcn_s_setprio(1); _Pragma("unroll") for (int m = 0; m < 4; ++m) _Pragma("unroll") for (int n = 0; n < 2; ++n) _Pragma("unroll") for (int k = 0; k < 2; ++k) \
;         acc[ai][bj][m][n] = __builtin_amdgcn_mfma_f32_16x16x32_bf16(Bt[n][k], At[m][k], acc[ai][bj][m][n], 0, 0, 0); __builtin_amdgcn_s_setprio(0); } while (0)
; #define PG8_WAIT_V(n) asm volatile("s_waitcnt vmcnt(" #n ")" ::: "memory")
; #define PG8_WAIT_L(n) asm volatile("s_waitcnt lgkmcnt(" #n ")" ::: "memory")
; #define PG8_BAR __builtin_amdgcn_s_barrier()
; #define PG8_SCHED __builtin_amdgcn_sched_barrier(0)
; __device__ __forceinline__ void gemm_phase(LAS unsigned char* lds, const Params& p, const bf16_t* gA, const bf16_t* gBt, const int gM, const int gN, const int gK, const int epi, const int perm, bf16_t* const Hp, const int goff, const float coef) {
;     ...
;             PG8_WAIT_V(8); PG8_WAIT_L(0); PG8_BAR; PG8_MMA(1, 0, At, B0); PG8_MMA(1, 1, At, B1); PG8_BAR; PG8_SCHED;
;             PG8_LDB(B0, 1, 0); PG8_LDB(B1, 1, 1); PG8_SCHED; PG8_LDA(At, 1, 0); PG8_STAGE(PG8_SA(0, 1), a2 + hstep, voffA);
;             PG8_WAIT_V(8); PG8_WAIT_L(0); PG8_BAR; PG8_MMA(0, 0, At, B0); PG8_MMA(0, 1, At, B1); PG8_BAR; PG8_SCHED;
	s_setprio 1
	s_waitcnt lgkmcnt(0)
	v_mfma_f32_16x16x32_bf16 v[60:63], v[160:163], v[192:195], v[60:63]
	v_mfma_f32_16x16x32_bf16 v[56:59], v[168:171], v[192:195], v[56:59]
	v_mfma_f32_16x16x32_bf16 v[44:47], v[160:163], v[200:203], v[44:47]
	v_mfma_f32_16x16x32_bf16 v[40:43], v[168:171], v[200:203], v[40:43]
	v_mfma_f32_16x16x32_bf16 v[28:31], v[160:163], v[208:211], v[28:31]
	v_mfma_f32_16x16x32_bf16 v[24:27], v[168:171], v[208:211], v[24:27]
	v_mfma_f32_16x16x32_bf16 v[12:15], v[160:163], v[216:219], v[12:15]
	v_mfma_f32_16x16x32_bf16 v[8:11], v[168:171], v[216:219], v[8:11]
	v_mfma_f32_16x16x32_bf16 v[60:63], v[164:167], v[196:199], v[60:63]
	v_mfma_f32_16x16x32_bf16 v[56:59], v[172:175], v[196:199], v[56:59]
	v_mfma_f32_16x16x32_bf16 v[44:47], v[164:167], v[204:207], v[44:47]
	v_mfma_f32_16x16x32_bf16 v[40:43], v[172:175], v[204:207], v[40:43]
	v_mfma_f32_16x16x32_bf16 v[28:31], v[164:167], v[212:215], v[28:31]
	v_mfma_f32_16x16x32_bf16 v[24:27], v[172:175], v[212:215], v[24:27]
	v_mfma_f32_16x16x32_bf16 v[12:15], v[164:167], v[220:223], v[12:15]
	v_mfma_f32_16x16x32_bf16 v[8:11], v[172:175], v[220:223], v[8:11]
	v_mfma_f32_16x16x32_bf16 v[52:55], v[176:179], v[192:195], v[52:55]
	v_mfma_f32_16x16x32_bf16 v[48:51], v[184:187], v[192:195], v[48:51]
	v_mfma_f32_16x16x32_bf16 v[36:39], v[176:179], v[200:203], v[36:39]
	v_mfma_f32_16x16x32_bf16 v[32:35], v[184:187], v[200:203], v[32:35]
	v_mfma_f32_16x16x32_bf16 v[20:23], v[176:179], v[208:211], v[20:23]
	v_mfma_f32_16x16x32_bf16 v[16:19], v[184:187], v[208:211], v[16:19]
	v_mfma_f32_16x16x32_bf16 v[4:7], v[176:179], v[216:219], v[4:7]
	v_mfma_f32_16x16x32_bf16 v[0:3], v[184:187], v[216:219], v[0:3]
	v_mfma_f32_16x16x32_bf16 v[52:55], v[180:183], v[196:199], v[52:55]
	v_mfma_f32_16x16x32_bf16 v[48:51], v[188:191], v[196:199], v[48:51]
	v_mfma_f32_16x16x32_bf16 v[36:39], v[180:183], v[204:207], v[36:39]
	v_mfma_f32_16x16x32_bf16 v[32:35], v[188:191], v[204:207], v[32:35]
	v_mfma_f32_16x16x32_bf16 v[20:23], v[180:183], v[212:215], v[20:23]
	v_mfma_f32_16x16x32_bf16 v[16:19], v[188:191], v[212:215], v[16:19]
	v_mfma_f32_16x16x32_bf16 v[4:7], v[180:183], v[220:223], v[4:7]
	v_mfma_f32_16x16x32_bf16 v[0:3], v[188:191], v[220:223], v[0:3]
	s_setprio 0
	s_barrier
	s_add_i32 s55, 0, 0x18000
	v_add_u32_e32 v141, s55, v147
	s_add_i32 s56, 0, 0x1c000
	ds_read_b128 v[160:163], v141
	ds_read_b128 v[164:167], v141 offset:1024
	ds_read_b128 v[168:171], v141 offset:2048
	ds_read_b128 v[172:175], v141 offset:3072
	v_add_u32_e32 v141, s56, v147
	ds_read_b128 v[176:179], v141
	ds_read_b128 v[180:183], v141 offset:1024
	ds_read_b128 v[184:187], v141 offset:2048
	ds_read_b128 v[188:191], v141 offset:3072
	s_add_u32 s30, s30, 0x80000
	s_addc_u32 s31, s31, 0
	s_mov_b32 m0, s37
	v_lshl_add_u64 v[230:231], s[30:31], 0, v[128:129]
	ds_read_b128 v[192:195], v158 offset:32768
	ds_read_b128 v[196:199], v158 offset:33792
	ds_read_b128 v[200:203], v158 offset:34816
	ds_read_b128 v[204:207], v158 offset:35840
	ds_read_b128 v[208:211], v158 offset:36864
	ds_read_b128 v[212:215], v158 offset:37888
	ds_read_b128 v[216:219], v158 offset:38912
	ds_read_b128 v[220:223], v158 offset:39936
	global_load_lds_dwordx4 v[230:231], off
	v_lshl_add_u64 v[230:231], s[30:31], 0, v[132:133]
	s_mov_b32 m0, s38
	s_nop 0
	global_load_lds_dwordx4 v[230:231], off
	s_waitcnt vmcnt(8)
	s_waitcnt lgkmcnt(0)
	s_barrier
	s_setprio 1
	s_waitcnt lgkmcnt(0)
	v_mfma_f32_16x16x32_bf16 v[124:127], v[160:163], v[192:195], v[124:127]
	v_mfma_f32_16x16x32_bf16 v[120:123], v[168:171], v[192:195], v[120:123]
	v_mfma_f32_16x16x32_bf16 v[108:111], v[160:163], v[200:203], v[108:111]
	v_mfma_f32_16x16x32_bf16 v[104:107], v[168:171], v[200:203], v[104:107]
	v_mfma_f32_16x16x32_bf16 v[92:95], v[160:163], v[208:211], v[92:95]
	v_mfma_f32_16x16x32_bf16 v[88:91], v[168:171], v[208:211], v[88:91]
	v_mfma_f32_16x16x32_bf16 v[76:79], v[160:163], v[216:219], v[76:79]
	v_mfma_f32_16x16x32_bf16 v[72:75], v[168:171], v[216:219], v[72:75]
	v_mfma_f32_16x16x32_bf16 v[124:127], v[164:167], v[196:199], v[124:127]
	v_mfma_f32_16x16x32_bf16 v[120:123], v[172:175], v[196:199], v[120:123]
	v_mfma_f32_16x16x32_bf16 v[108:111], v[164:167], v[204:207], v[108:111]
	v_mfma_f32_16x16x32_bf16 v[104:107], v[172:175], v[204:207], v[104:107]
	v_mfma_f32_16x16x32_bf16 v[92:95], v[164:167], v[212:215], v[92:95]
	v_mfma_f32_16x16x32_bf16 v[88:91], v[172:175], v[212:215], v[88:91]
	v_mfma_f32_16x16x32_bf16 v[76:79], v[164:167], v[220:223], v[76:79]
	v_mfma_f32_16x16x32_bf16 v[72:75], v[172:175], v[220:223], v[72:75]
	v_mfma_f32_16x16x32_bf16 v[116:119], v[176:179], v[192:195], v[116:119]
	v_mfma_f32_16x16x32_bf16 v[112:115], v[184:187], v[192:195], v[112:115]
	v_mfma_f32_16x16x32_bf16 v[100:103], v[176:179], v[200:203], v[100:103]
	v_mfma_f32_16x16x32_bf16 v[96:99], v[184:187], v[200:203], v[96:99]
	v_mfma_f32_16x16x32_bf16 v[84:87], v[176:179], v[208:211], v[84:87]
	v_mfma_f32_16x16x32_bf16 v[80:83], v[184:187], v[208:211], v[80:83]
	v_mfma_f32_16x16x32_bf16 v[68:71], v[176:179], v[216:219], v[68:71]
	v_mfma_f32_16x16x32_bf16 v[64:67], v[184:187], v[216:219], v[64:67]
	v_mfma_f32_16x16x32_bf16 v[116:119], v[180:183], v[196:199], v[116:119]
	v_mfma_f32_16x16x32_bf16 v[112:115], v[188:191], v[196:199], v[112:115]
	v_mfma_f32_16x16x32_bf16 v[100:103], v[180:183], v[204:207], v[100:103]
	v_mfma_f32_16x16x32_bf16 v[96:99], v[188:191], v[204:207], v[96:99]
	v_mfma_f32_16x16x32_bf16 v[84:87], v[180:183], v[212:215], v[84:87]
	v_mfma_f32_16x16x32_bf16 v[80:83], v[188:191], v[212:215], v[80:83]
	v_mfma_f32_16x16x32_bf16 v[68:71], v[180:183], v[220:223], v[68:71]
	v_mfma_f32_16x16x32_bf16 v[64:67], v[188:191], v[220:223], v[64:67]
	s_setprio 0
	s_barrier
; #define PG8_STAGE(bufoff, gbase, voff) do { _Pragma("unroll") for (int _i = 0; _i < 2; ++_i) \
;         __builtin_amdgcn_global_load_lds((const unsigned*)((const char*)(gbase) + (voff)[_i]), (LAS unsigned*)(lds + (bufoff) + ldsw + _i * 8192), 16, 0, 0); } while (0)
; #define PG8_LDA(dst, b, h) do { _Pragma("unroll") for (int m = 0; m < 4; ++m) _Pragma("unroll") for (int k = 0; k < 2; ++k) dst[m][k] = *(const LAS bf16x8*)(lds + PG8_SA(b, h) + aoff + m * 2048 + k * 1024); } while (0)
; #define PG8_MMA(ai, bj, At, Bt) do { __builtin_amdgcn_s_setprio(1); _Pragma("unroll") for (int m = 0; m < 4; ++m) _Pragma("unroll") for (int n = 0; n < 2; ++n) _Pragma("unroll") for (int k = 0; k < 2; ++k) \
;         acc[ai][bj][m][n] = __builtin_amdgcn_mfma_f32_16x16x32_bf16(Bt[n][k], At[m][k], acc[ai][bj][m][n], 0, 0, 0); __builtin_amdgcn_s_setprio(0); } while (0)
; #define PG8_WAIT_V(n) asm volatile("s_waitcnt vmcnt(" #n ")" ::: "memory")
; #define PG8_WAIT_L(n) asm volatile("s_waitcnt lgkmcnt(" #n ")" ::: "memory")
; #define PG8_BAR __builtin_amdgcn_s_barrier()
; #define PG8_SCHED __builtin_amdgcn_sched_barrier(0)
; __device__ __forceinline__ void gemm_phase(LAS unsigned char* lds, const Params& p, const bf16_t* gA, const bf16_t* gBt, const int gM, const int gN, const int gK, const int epi, const int perm, bf16_t* const Hp, const int goff, const float coef) {
;     ...
;             PG8_LDA(At, 1, 1); PG8_STAGE(PG8_SB(1, 0), b3, voffB); PG8_STAGE(PG8_SB(1, 1), b3 + hstep, voffB); PG8_STAGE(PG8_SA(1, 0), a3, voffA);
;             PG8_WAIT_V(8); PG8_WAIT_L(0); PG8_BAR; PG8_MMA(1, 0, At, B0); PG8_MMA(1, 1, At, B1); PG8_BAR; PG8_SCHED;
;         }
;         if (wr == 0) PG8_BAR;
	s_add_i32 s30, s55, s36
	v_lshl_add_u64 v[144:145], v[144:145], 0, s[8:9]
	s_mov_b32 m0, s30
	ds_read_b128 v[192:195], v158 offset:49152
	ds_read_b128 v[196:199], v158 offset:50176
	ds_read_b128 v[200:203], v158 offset:51200
	ds_read_b128 v[204:207], v158 offset:52224
	ds_read_b128 v[208:211], v158 offset:53248
	ds_read_b128 v[212:215], v158 offset:54272
	ds_read_b128 v[216:219], v158 offset:55296
	ds_read_b128 v[220:223], v158 offset:56320
	global_load_lds_dwordx4 v[144:145], off
	s_add_i32 m0, s30, 0x2000
	s_add_u32 s28, s28, 0x80080
	v_lshl_add_u64 v[144:145], v[224:225], 0, s[8:9]
	s_addc_u32 s29, s29, 0
	s_add_i32 s30, s56, s36
	global_load_lds_dwordx4 v[144:145], off
	v_lshl_add_u64 v[144:145], s[28:29], 0, v[130:131]
	s_mov_b32 m0, s30
	s_nop 0
	global_load_lds_dwordx4 v[144:145], off
	v_lshl_add_u64 v[144:145], s[28:29], 0, v[134:135]
	s_add_i32 m0, s30, 0x2000
	s_nop 0
	global_load_lds_dwordx4 v[144:145], off
	v_lshl_add_u64 v[144:145], v[226:227], 0, s[8:9]
	s_mov_b32 m0, s40
	s_nop 0
	global_load_lds_dwordx4 v[144:145], off
	v_lshl_add_u64 v[144:145], v[228:229], 0, s[8:9]
	s_mov_b32 m0, s41
	s_nop 0
	global_load_lds_dwordx4 v[144:145], off
	s_waitcnt vmcnt(8)
	s_waitcnt lgkmcnt(0)
	s_barrier
	s_setprio 1
	s_waitcnt lgkmcnt(0)
	v_mfma_f32_16x16x32_bf16 v[60:63], v[160:163], v[192:195], v[60:63]
	v_mfma_f32_16x16x32_bf16 v[56:59], v[168:171], v[192:195], v[56:59]
	v_mfma_f32_16x16x32_bf16 v[44:47], v[160:163], v[200:203], v[44:47]
	v_mfma_f32_16x16x32_bf16 v[40:43], v[168:171], v[200:203], v[40:43]
	v_mfma_f32_16x16x32_bf16 v[28:31], v[160:163], v[208:211], v[28:31]
	v_mfma_f32_16x16x32_bf16 v[24:27], v[168:171], v[208:211], v[24:27]
	v_mfma_f32_16x16x32_bf16 v[12:15], v[160:163], v[216:219], v[12:15]
	v_mfma_f32_16x16x32_bf16 v[8:11], v[168:171], v[216:219], v[8:11]
	v_mfma_f32_16x16x32_bf16 v[60:63], v[164:167], v[196:199], v[60:63]
	v_mfma_f32_16x16x32_bf16 v[56:59], v[172:175], v[196:199], v[56:59]
	v_mfma_f32_16x16x32_bf16 v[44:47], v[164:167], v[204:207], v[44:47]
	v_mfma_f32_16x16x32_bf16 v[40:43], v[172:175], v[204:207], v[40:43]
	v_mfma_f32_16x16x32_bf16 v[28:31], v[164:167], v[212:215], v[28:31]
	v_mfma_f32_16x16x32_bf16 v[24:27], v[172:175], v[212:215], v[24:27]
	v_mfma_f32_16x16x32_bf16 v[12:15], v[164:167], v[220:223], v[12:15]
	v_mfma_f32_16x16x32_bf16 v[8:11], v[172:175], v[220:223], v[8:11]
	v_mfma_f32_16x16x32_bf16 v[52:55], v[176:179], v[192:195], v[52:55]
	v_mfma_f32_16x16x32_bf16 v[48:51], v[184:187], v[192:195], v[48:51]
	v_mfma_f32_16x16x32_bf16 v[36:39], v[176:179], v[200:203], v[36:39]
	v_mfma_f32_16x16x32_bf16 v[32:35], v[184:187], v[200:203], v[32:35]
	v_mfma_f32_16x16x32_bf16 v[20:23], v[176:179], v[208:211], v[20:23]
	v_mfma_f32_16x16x32_bf16 v[16:19], v[184:187], v[208:211], v[16:19]
	v_mfma_f32_16x16x32_bf16 v[4:7], v[176:179], v[216:219], v[4:7]
	v_mfma_f32_16x16x32_bf16 v[0:3], v[184:187], v[216:219], v[0:3]
	v_mfma_f32_16x16x32_bf16 v[52:55], v[180:183], v[196:199], v[52:55]
	v_mfma_f32_16x16x32_bf16 v[48:51], v[188:191], v[196:199], v[48:51]
	v_mfma_f32_16x16x32_bf16 v[36:39], v[180:183], v[204:207], v[36:39]
	v_mfma_f32_16x16x32_bf16 v[32:35], v[188:191], v[204:207], v[32:35]
	v_mfma_f32_16x16x32_bf16 v[20:23], v[180:183], v[212:215], v[20:23]
	v_mfma_f32_16x16x32_bf16 v[16:19], v[188:191], v[212:215], v[16:19]
	v_mfma_f32_16x16x32_bf16 v[4:7], v[180:183], v[220:223], v[4:7]
	v_mfma_f32_16x16x32_bf16 v[0:3], v[188:191], v[220:223], v[0:3]
	s_setprio 0
	s_barrier
	s_add_u32 s26, s26, 0x100
	s_addc_u32 s27, s27, 0
	s_add_u32 s52, s52, 0x100
	s_addc_u32 s53, s53, 0
	s_cmp_ge_u32 s54, s50
	s_mov_b32 s30, s54
	s_cbranch_scc0 .LBB0_1737
	s_and_b64 vcc, exec, s[10:11]
	s_cbranch_vccz .LBB0_1740
	s_barrier

; #define PG8_STAGE(bufoff, gbase, voff) do { _Pragma("unroll") for (int _i = 0; _i < 2; ++_i) \
;         __builtin_amdgcn_global_load_lds((const unsigned*)((const char*)(gbase) + (voff)[_i]), (LAS unsigned*)(lds + (bufoff) + ldsw + _i * 8192), 16, 0, 0); } while (0)
; #define PG8_LDA(dst, b, h) do { _Pragma("unroll") for (int m = 0; m < 4; ++m) _Pragma("unroll") for (int k = 0; k < 2; ++k) dst[m][k] = *(const LAS bf16x8*)(lds + PG8_SA(b, h) + aoff + m * 2048 + k * 1024); } while (0)
; #define PG8_LDB(dst, b, h) do { _Pragma("unroll") for (int n = 0; n < 2; ++n) _Pragma("unroll") for (int k = 0; k < 2; ++k) dst[n][k] = *(const LAS bf16x8*)(lds + PG8_SB(b, h) + boff + n * 2048 + k * 1024); } while (0)
; #define PG8_MMA(ai, bj, At, Bt) do { __builtin_amdgcn_s_setprio(1); _Pragma("unroll") for (int m = 0; m < 4; ++m) _Pragma("unroll") for (int n = 0; n < 2; ++n) _Pragma("unroll") for (int k = 0; k < 2; ++k) \
;         acc[ai][bj][m][n] = __builtin_amdgcn_mfma_f32_16x16x32_bf16(Bt[n][k], At[m][k], acc[ai][bj][m][n], 0, 0, 0); __builtin_amdgcn_s_setprio(0); } while (0)
; #define PG8_WAIT_V(n) asm volatile("s_waitcnt vmcnt(" #n ")" ::: "memory")
; #define PG8_WAIT_L(n) asm volatile("s_waitcnt lgkmcnt(" #n ")" ::: "memory")
; #define PG8_BAR __builtin_amdgcn_s_barrier()
; #define PG8_SCHED __builtin_amdgcn_sched_barrier(0)
; __device__ __forceinline__ void gemm_phase(LAS unsigned char* lds, const Params& p, const bf16_t* gA, const bf16_t* gBt, const int gM, const int gN, const int gK, const int epi, const int perm, bf16_t* const Hp, const int goff, const float coef) {
;     ...
;         for (int t = 0; t < nt; t += 2) {
;             const bool last = (t == nt - 2);
;             const char* a1 = cA + (size_t)(t + 1) * kstep;
;             const char* a2 = last ? nA : cA + (size_t)(t + 2) * kstep; const char* b2 = last ? nB : cB + (size_t)(t + 2) * kstep;
;             const char* a3 = a2 + kstep; const char* b3 = b2 + kstep;
;             PG8_LDB(B0, 0, 0); PG8_LDB(B1, 0, 1); PG8_SCHED; PG8_LDA(At, 0, 0); PG8_STAGE(PG8_SA(1, 1), a1 + hstep, voffA);
;             PG8_WAIT_V(8); PG8_WAIT_L(0); PG8_BAR; PG8_MMA(0, 0, At, B0); PG8_MMA(0, 1, At, B1); PG8_BAR; PG8_SCHED;
;             PG8_LDA(At, 0, 1); PG8_STAGE(PG8_SB(0, 0), b2, voffB); PG8_STAGE(PG8_SB(0, 1), b2 + hstep, voffB); PG8_STAGE(PG8_SA(0, 0), a2, voffA);
.LBB0_1827:
	ds_read_b128 v[144:147], v166
	ds_read_b128 v[148:151], v166 offset:1024
	ds_read_b128 v[152:155], v166 offset:2048
	ds_read_b128 v[170:173], v166 offset:3072
	ds_read_b128 v[174:177], v167
	ds_read_b128 v[178:181], v167 offset:1024
	ds_read_b128 v[182:185], v167 offset:2048
	ds_read_b128 v[186:189], v167 offset:3072
	s_add_i32 s54, s20, 2
	s_add_u32 s21, s18, 0xffea0080
	s_addc_u32 s22, s19, -1
	s_cmp_eq_u32 s51, s20
	s_cselect_b32 s20, s16, s52
	s_cselect_b32 s23, s15, s22
	s_cselect_b32 s22, s14, s21
	s_cselect_b32 s21, s17, s53
	v_lshl_add_u64 v[222:223], s[18:19], 0, v[136:137]
	s_add_i32 m0, s28, 0xc000
	ds_read_b128 v[190:193], v168
	ds_read_b128 v[194:197], v168 offset:1024
	ds_read_b128 v[198:201], v168 offset:2048
	ds_read_b128 v[202:205], v168 offset:3072
	ds_read_b128 v[206:209], v168 offset:4096
	ds_read_b128 v[210:213], v168 offset:5120
	ds_read_b128 v[214:217], v168 offset:6144
	ds_read_b128 v[218:221], v168 offset:7168
	global_load_lds_dwordx4 v[222:223], off
	v_lshl_add_u64 v[222:223], s[18:19], 0, v[138:139]
	s_add_i32 m0, s28, 0xe000
	s_nop 0
	global_load_lds_dwordx4 v[222:223], off
	s_waitcnt vmcnt(8)
	s_waitcnt lgkmcnt(0)
	s_barrier
	s_setprio 1
	s_waitcnt lgkmcnt(0)
	v_mfma_f32_16x16x32_bf16 v[124:127], v[144:147], v[190:193], v[124:127]
	v_mfma_f32_16x16x32_bf16 v[120:123], v[152:155], v[190:193], v[120:123]
	v_mfma_f32_16x16x32_bf16 v[116:119], v[144:147], v[198:201], v[116:119]
	v_mfma_f32_16x16x32_bf16 v[112:115], v[152:155], v[198:201], v[112:115]
	v_mfma_f32_16x16x32_bf16 v[108:111], v[144:147], v[206:209], v[108:111]
	v_mfma_f32_16x16x32_bf16 v[104:107], v[152:155], v[206:209], v[104:107]
	v_mfma_f32_16x16x32_bf16 v[100:103], v[144:147], v[214:217], v[100:103]
	v_mfma_f32_16x16x32_bf16 v[96:99], v[152:155], v[214:217], v[96:99]
	v_mfma_f32_16x16x32_bf16 v[124:127], v[148:151], v[194:197], v[124:127]
	v_mfma_f32_16x16x32_bf16 v[120:123], v[170:173], v[194:197], v[120:123]
	v_mfma_f32_16x16x32_bf16 v[116:119], v[148:151], v[202:205], v[116:119]
	v_mfma_f32_16x16x32_bf16 v[112:115], v[170:173], v[202:205], v[112:115]
	v_mfma_f32_16x16x32_bf16 v[108:111], v[148:151], v[210:213], v[108:111]
	v_mfma_f32_16x16x32_bf16 v[104:107], v[170:173], v[210:213], v[104:107]
	v_mfma_f32_16x16x32_bf16 v[100:103], v[148:151], v[218:221], v[100:103]
	v_mfma_f32_16x16x32_bf16 v[96:99], v[170:173], v[218:221], v[96:99]
	v_mfma_f32_16x16x32_bf16 v[68:71], v[174:177], v[190:193], v[68:71]
	v_mfma_f32_16x16x32_bf16 v[60:63], v[182:185], v[190:193], v[60:63]
	v_mfma_f32_16x16x32_bf16 v[52:55], v[174:177], v[198:201], v[52:55]
	v_mfma_f32_16x16x32_bf16 v[48:51], v[182:185], v[198:201], v[48:51]
	v_mfma_f32_16x16x32_bf16 v[44:47], v[174:177], v[206:209], v[44:47]
	v_mfma_f32_16x16x32_bf16 v[40:43], v[182:185], v[206:209], v[40:43]
	v_mfma_f32_16x16x32_bf16 v[36:39], v[174:177], v[214:217], v[36:39]
	v_mfma_f32_16x16x32_bf16 v[32:35], v[182:185], v[214:217], v[32:35]
	v_mfma_f32_16x16x32_bf16 v[68:71], v[178:181], v[194:197], v[68:71]
	v_mfma_f32_16x16x32_bf16 v[60:63], v[186:189], v[194:197], v[60:63]
	v_mfma_f32_16x16x32_bf16 v[52:55], v[178:181], v[202:205], v[52:55]
	v_mfma_f32_16x16x32_bf16 v[48:51], v[186:189], v[202:205], v[48:51]
	v_mfma_f32_16x16x32_bf16 v[44:47], v[178:181], v[210:213], v[44:47]
	v_mfma_f32_16x16x32_bf16 v[40:43], v[186:189], v[210:213], v[40:43]
	v_mfma_f32_16x16x32_bf16 v[36:39], v[178:181], v[218:221], v[36:39]
	v_mfma_f32_16x16x32_bf16 v[32:35], v[186:189], v[218:221], v[32:35]
	s_setprio 0
	s_barrier
	s_add_i32 s55, s42, s27
	v_lshl_add_u64 v[222:223], s[20:21], 0, v[130:131]
	s_mov_b32 m0, s55
	ds_read_b128 v[190:193], v168 offset:16384
	ds_read_b128 v[194:197], v168 offset:17408
	ds_read_b128 v[198:201], v168 offset:18432
	ds_read_b128 v[202:205], v168 offset:19456
	ds_read_b128 v[206:209], v168 offset:20480
	ds_read_b128 v[210:213], v168 offset:21504
	ds_read_b128 v[214:217], v168 offset:22528
	ds_read_b128 v[218:221], v168 offset:23552
	global_load_lds_dwordx4 v[222:223], off
	s_add_i32 m0, s55, 0x2000
	s_add_u32 s56, s20, 0x160000
	v_lshl_add_u64 v[224:225], s[20:21], 0, v[134:135]
	s_addc_u32 s57, s21, 0
	s_add_i32 s55, s43, s27
	global_load_lds_dwordx4 v[224:225], off
	v_lshl_add_u64 v[226:227], s[56:57], 0, v[130:131]
	s_mov_b32 m0, s55
	v_lshl_add_u64 v[228:229], s[22:23], 0, v[132:133]
	global_load_lds_dwordx4 v[226:227], off
	v_lshl_add_u64 v[226:227], s[56:57], 0, v[134:135]
	s_add_i32 m0, s55, 0x2000
	s_nop 0
	global_load_lds_dwordx4 v[226:227], off
	v_lshl_add_u64 v[226:227], s[22:23], 0, v[128:129]
	s_mov_b32 m0, s28
	s_nop 0
	global_load_lds_dwordx4 v[226:227], off
	s_mov_b32 m0, s29
	s_nop 0
	global_load_lds_dwordx4 v[228:229], off
	s_waitcnt vmcnt(8)
	s_waitcnt lgkmcnt(0)
	s_barrier
; #define PG8_STAGE(bufoff, gbase, voff) do { _Pragma("unroll") for (int _i = 0; _i < 2; ++_i) \
;         __builtin_amdgcn_global_load_lds((const unsigned*)((const char*)(gbase) + (voff)[_i]), (LAS unsigned*)(lds + (bufoff) + ldsw + _i * 8192), 16, 0, 0); } while (0)
; #define PG8_LDA(dst, b, h) do { _Pragma("unroll") for (int m = 0; m < 4; ++m) _Pragma("unroll") for (int k = 0; k < 2; ++k) dst[m][k] = *(const LAS bf16x8*)(lds + PG8_SA(b, h) + aoff + m * 2048 + k * 1024); } while (0)
; #define PG8_LDB(dst, b, h) do { _Pragma("unroll") for (int n = 0; n < 2; ++n) _Pragma("unroll") for (int k = 0; k < 2; ++k) dst[n][k] = *(const LAS bf16x8*)(lds + PG8_SB(b, h) + boff + n * 2048 + k * 1024); } while (0)
; #define PG8_MMA(ai, bj, At, Bt) do { __builtin_amdgcn_s_setprio(1); _Pragma("unroll") for (int m = 0; m < 4; ++m) _Pragma("unroll") for (int n = 0; n < 2; ++n) _Pragma("unroll") for (int k = 0; k < 2; ++k) \
;         acc[ai][bj][m][n] = __builtin_amdgcn_mfma_f32_16x16x32_bf16(Bt[n][k], At[m][k], acc[ai][bj][m][n], 0, 0, 0); __builtin_amdgcn_s_setprio(0); } while (0)
; #define PG8_WAIT_V(n) asm volatile("s_waitcnt vmcnt(" #n ")" ::: "memory")
; #define PG8_WAIT_L(n) asm volatile("s_waitcnt lgkmcnt(" #n ")" ::: "memory")
; #define PG8_BAR __builtin_amdgcn_s_barrier()
; #define PG8_SCHED __builtin_amdgcn_sched_barrier(0)
; __device__ __forceinline__ void gemm_phase(LAS unsigned char* lds, const Params& p, const bf16_t* gA, const bf16_t* gBt, const int gM, const int gN, const int gK, const int epi, const int perm, bf16_t* const Hp, const int goff, const float coef) {
;     ...
;             PG8_WAIT_V(8); PG8_WAIT_L(0); PG8_BAR; PG8_MMA(1, 0, At, B0); PG8_MMA(1, 1, At, B1); PG8_BAR; PG8_SCHED;
;             PG8_LDB(B0, 1, 0); PG8_LDB(B1, 1, 1); PG8_SCHED; PG8_LDA(At, 1, 0); PG8_STAGE(PG8_SA(0, 1), a2 + hstep, voffA);
;             PG8_WAIT_V(8); PG8_WAIT_L(0); PG8_BAR; PG8_MMA(0, 0, At, B0); PG8_MMA(0, 1, At, B1); PG8_BAR; PG8_SCHED;
	s_setprio 1
	s_waitcnt lgkmcnt(0)
	v_mfma_f32_16x16x32_bf16 v[92:95], v[144:147], v[190:193], v[92:95]
	v_mfma_f32_16x16x32_bf16 v[88:91], v[152:155], v[190:193], v[88:91]
	v_mfma_f32_16x16x32_bf16 v[84:87], v[144:147], v[198:201], v[84:87]
	v_mfma_f32_16x16x32_bf16 v[80:83], v[152:155], v[198:201], v[80:83]
	v_mfma_f32_16x16x32_bf16 v[76:79], v[144:147], v[206:209], v[76:79]
	v_mfma_f32_16x16x32_bf16 v[72:75], v[152:155], v[206:209], v[72:75]
	v_mfma_f32_16x16x32_bf16 v[64:67], v[144:147], v[214:217], v[64:67]
	v_mfma_f32_16x16x32_bf16 v[56:59], v[152:155], v[214:217], v[56:59]
	v_mfma_f32_16x16x32_bf16 v[92:95], v[148:151], v[194:197], v[92:95]
	v_mfma_f32_16x16x32_bf16 v[88:91], v[170:173], v[194:197], v[88:91]
	v_mfma_f32_16x16x32_bf16 v[84:87], v[148:151], v[202:205], v[84:87]
	v_mfma_f32_16x16x32_bf16 v[80:83], v[170:173], v[202:205], v[80:83]
	v_mfma_f32_16x16x32_bf16 v[76:79], v[148:151], v[210:213], v[76:79]
	v_mfma_f32_16x16x32_bf16 v[72:75], v[170:173], v[210:213], v[72:75]
	v_mfma_f32_16x16x32_bf16 v[64:67], v[148:151], v[218:221], v[64:67]
	v_mfma_f32_16x16x32_bf16 v[56:59], v[170:173], v[218:221], v[56:59]
	v_mfma_f32_16x16x32_bf16 v[28:31], v[174:177], v[190:193], v[28:31]
	v_mfma_f32_16x16x32_bf16 v[24:27], v[182:185], v[190:193], v[24:27]
	v_mfma_f32_16x16x32_bf16 v[20:23], v[174:177], v[198:201], v[20:23]
	v_mfma_f32_16x16x32_bf16 v[16:19], v[182:185], v[198:201], v[16:19]
	v_mfma_f32_16x16x32_bf16 v[12:15], v[174:177], v[206:209], v[12:15]
	v_mfma_f32_16x16x32_bf16 v[8:11], v[182:185], v[206:209], v[8:11]
	v_mfma_f32_16x16x32_bf16 v[4:7], v[174:177], v[214:217], v[4:7]
	v_mfma_f32_16x16x32_bf16 v[0:3], v[182:185], v[214:217], v[0:3]
	v_mfma_f32_16x16x32_bf16 v[28:31], v[178:181], v[194:197], v[28:31]
	v_mfma_f32_16x16x32_bf16 v[24:27], v[186:189], v[194:197], v[24:27]
	v_mfma_f32_16x16x32_bf16 v[20:23], v[178:181], v[202:205], v[20:23]
	v_mfma_f32_16x16x32_bf16 v[16:19], v[186:189], v[202:205], v[16:19]
	v_mfma_f32_16x16x32_bf16 v[12:15], v[178:181], v[210:213], v[12:15]
	v_mfma_f32_16x16x32_bf16 v[8:11], v[186:189], v[210:213], v[8:11]
	v_mfma_f32_16x16x32_bf16 v[4:7], v[178:181], v[218:221], v[4:7]
	v_mfma_f32_16x16x32_bf16 v[0:3], v[186:189], v[218:221], v[0:3]
	s_setprio 0
	s_barrier
	s_add_i32 s55, 0, 0x18000
	v_add_u32_e32 v141, s55, v157
	s_add_i32 s56, 0, 0x1c000
	ds_read_b128 v[144:147], v141
	ds_read_b128 v[148:151], v141 offset:1024
	ds_read_b128 v[152:155], v141 offset:2048
	ds_read_b128 v[170:173], v141 offset:3072
	v_add_u32_e32 v141, s56, v157
	ds_read_b128 v[174:177], v141
	ds_read_b128 v[178:181], v141 offset:1024
	ds_read_b128 v[182:185], v141 offset:2048
	ds_read_b128 v[186:189], v141 offset:3072
	s_add_u32 s22, s22, 0x160000
	s_addc_u32 s23, s23, 0
	s_mov_b32 m0, s30
	v_lshl_add_u64 v[230:231], s[22:23], 0, v[128:129]
	ds_read_b128 v[190:193], v168 offset:32768
	ds_read_b128 v[194:197], v168 offset:33792
	ds_read_b128 v[198:201], v168 offset:34816
	ds_read_b128 v[202:205], v168 offset:35840
	ds_read_b128 v[206:209], v168 offset:36864
	ds_read_b128 v[210:213], v168 offset:37888
	ds_read_b128 v[214:217], v168 offset:38912
	ds_read_b128 v[218:221], v168 offset:39936
	global_load_lds_dwordx4 v[230:231], off
	v_lshl_add_u64 v[230:231], s[22:23], 0, v[132:133]
	s_mov_b32 m0, s31
	s_nop 0
	global_load_lds_dwordx4 v[230:231], off
	s_waitcnt vmcnt(8)
	s_waitcnt lgkmcnt(0)
	s_barrier
	s_setprio 1
	s_waitcnt lgkmcnt(0)
	v_mfma_f32_16x16x32_bf16 v[124:127], v[144:147], v[190:193], v[124:127]
	v_mfma_f32_16x16x32_bf16 v[120:123], v[152:155], v[190:193], v[120:123]
	v_mfma_f32_16x16x32_bf16 v[116:119], v[144:147], v[198:201], v[116:119]
	v_mfma_f32_16x16x32_bf16 v[112:115], v[152:155], v[198:201], v[112:115]
	v_mfma_f32_16x16x32_bf16 v[108:111], v[144:147], v[206:209], v[108:111]
	v_mfma_f32_16x16x32_bf16 v[104:107], v[152:155], v[206:209], v[104:107]
	v_mfma_f32_16x16x32_bf16 v[100:103], v[144:147], v[214:217], v[100:103]
	v_mfma_f32_16x16x32_bf16 v[96:99], v[152:155], v[214:217], v[96:99]
	v_mfma_f32_16x16x32_bf16 v[124:127], v[148:151], v[194:197], v[124:127]
	v_mfma_f32_16x16x32_bf16 v[120:123], v[170:173], v[194:197], v[120:123]
	v_mfma_f32_16x16x32_bf16 v[116:119], v[148:151], v[202:205], v[116:119]
	v_mfma_f32_16x16x32_bf16 v[112:115], v[170:173], v[202:205], v[112:115]
	v_mfma_f32_16x16x32_bf16 v[108:111], v[148:151], v[210:213], v[108:111]
	v_mfma_f32_16x16x32_bf16 v[104:107], v[170:173], v[210:213], v[104:107]
	v_mfma_f32_16x16x32_bf16 v[100:103], v[148:151], v[218:221], v[100:103]
	v_mfma_f32_16x16x32_bf16 v[96:99], v[170:173], v[218:221], v[96:99]
	v_mfma_f32_16x16x32_bf16 v[68:71], v[174:177], v[190:193], v[68:71]
	v_mfma_f32_16x16x32_bf16 v[60:63], v[182:185], v[190:193], v[60:63]
	v_mfma_f32_16x16x32_bf16 v[52:55], v[174:177], v[198:201], v[52:55]
	v_mfma_f32_16x16x32_bf16 v[48:51], v[182:185], v[198:201], v[48:51]
	v_mfma_f32_16x16x32_bf16 v[44:47], v[174:177], v[206:209], v[44:47]
	v_mfma_f32_16x16x32_bf16 v[40:43], v[182:185], v[206:209], v[40:43]
	v_mfma_f32_16x16x32_bf16 v[36:39], v[174:177], v[214:217], v[36:39]
	v_mfma_f32_16x16x32_bf16 v[32:35], v[182:185], v[214:217], v[32:35]
	v_mfma_f32_16x16x32_bf16 v[68:71], v[178:181], v[194:197], v[68:71]
	v_mfma_f32_16x16x32_bf16 v[60:63], v[186:189], v[194:197], v[60:63]
	v_mfma_f32_16x16x32_bf16 v[52:55], v[178:181], v[202:205], v[52:55]
	v_mfma_f32_16x16x32_bf16 v[48:51], v[186:189], v[202:205], v[48:51]
	v_mfma_f32_16x16x32_bf16 v[44:47], v[178:181], v[210:213], v[44:47]
	v_mfma_f32_16x16x32_bf16 v[40:43], v[186:189], v[210:213], v[40:43]
	v_mfma_f32_16x16x32_bf16 v[36:39], v[178:181], v[218:221], v[36:39]
	v_mfma_f32_16x16x32_bf16 v[32:35], v[186:189], v[218:221], v[32:35]
	s_setprio 0
	s_barrier
; #define PG8_STAGE(bufoff, gbase, voff) do { _Pragma("unroll") for (int _i = 0; _i < 2; ++_i) \
;         __builtin_amdgcn_global_load_lds((const unsigned*)((const char*)(gbase) + (voff)[_i]), (LAS unsigned*)(lds + (bufoff) + ldsw + _i * 8192), 16, 0, 0); } while (0)
; #define PG8_LDA(dst, b, h) do { _Pragma("unroll") for (int m = 0; m < 4; ++m) _Pragma("unroll") for (int k = 0; k < 2; ++k) dst[m][k] = *(const LAS bf16x8*)(lds + PG8_SA(b, h) + aoff + m * 2048 + k * 1024); } while (0)
; #define PG8_MMA(ai, bj, At, Bt) do { __builtin_amdgcn_s_setprio(1); _Pragma("unroll") for (int m = 0; m < 4; ++m) _Pragma("unroll") for (int n = 0; n < 2; ++n) _Pragma("unroll") for (int k = 0; k < 2; ++k) \
;         acc[ai][bj][m][n] = __builtin_amdgcn_mfma_f32_16x16x32_bf16(Bt[n][k], At[m][k], acc[ai][bj][m][n], 0, 0, 0); __builtin_amdgcn_s_setprio(0); } while (0)
; #define PG8_WAIT_V(n) asm volatile("s_waitcnt vmcnt(" #n ")" ::: "memory")
; #define PG8_WAIT_L(n) asm volatile("s_waitcnt lgkmcnt(" #n ")" ::: "memory")
; #define PG8_BAR __builtin_amdgcn_s_barrier()
; #define PG8_SCHED __builtin_amdgcn_sched_barrier(0)
; __device__ __forceinline__ void gemm_phase(LAS unsigned char* lds, const Params& p, const bf16_t* gA, const bf16_t* gBt, const int gM, const int gN, const int gK, const int epi, const int perm, bf16_t* const Hp, const int goff, const float coef) {
;     ...
;             PG8_LDA(At, 1, 1); PG8_STAGE(PG8_SB(1, 0), b3, voffB); PG8_STAGE(PG8_SB(1, 1), b3 + hstep, voffB); PG8_STAGE(PG8_SA(1, 0), a3, voffA);
;             PG8_WAIT_V(8); PG8_WAIT_L(0); PG8_BAR; PG8_MMA(1, 0, At, B0); PG8_MMA(1, 1, At, B1); PG8_BAR; PG8_SCHED;
;         }
;         if (wr == 0) PG8_BAR;
	s_add_i32 s22, s55, s27
	v_lshl_add_u64 v[222:223], v[222:223], 0, s[10:11]
	s_mov_b32 m0, s22
	ds_read_b128 v[190:193], v168 offset:49152
	ds_read_b128 v[194:197], v168 offset:50176
	ds_read_b128 v[198:201], v168 offset:51200
	ds_read_b128 v[202:205], v168 offset:52224
	ds_read_b128 v[206:209], v168 offset:53248
	ds_read_b128 v[210:213], v168 offset:54272
	ds_read_b128 v[214:217], v168 offset:55296
	ds_read_b128 v[218:221], v168 offset:56320
	global_load_lds_dwordx4 v[222:223], off
	s_add_i32 m0, s22, 0x2000
	s_add_u32 s20, s20, 0x160080
	v_lshl_add_u64 v[222:223], v[224:225], 0, s[10:11]
	s_addc_u32 s21, s21, 0
	s_add_i32 s22, s56, s27
	global_load_lds_dwordx4 v[222:223], off
	v_lshl_add_u64 v[222:223], s[20:21], 0, v[130:131]
	s_mov_b32 m0, s22
	s_nop 0
	global_load_lds_dwordx4 v[222:223], off
	v_lshl_add_u64 v[222:223], s[20:21], 0, v[134:135]
	s_add_i32 m0, s22, 0x2000
	s_nop 0
	global_load_lds_dwordx4 v[222:223], off
	v_lshl_add_u64 v[222:223], v[226:227], 0, s[10:11]
	s_mov_b32 m0, s36
	s_nop 0
	global_load_lds_dwordx4 v[222:223], off
	v_lshl_add_u64 v[222:223], v[228:229], 0, s[10:11]
	s_mov_b32 m0, s37
	s_nop 0
	global_load_lds_dwordx4 v[222:223], off
	s_waitcnt vmcnt(8)
	s_waitcnt lgkmcnt(0)
	s_barrier
	s_setprio 1
	s_waitcnt lgkmcnt(0)
	v_mfma_f32_16x16x32_bf16 v[92:95], v[144:147], v[190:193], v[92:95]
	v_mfma_f32_16x16x32_bf16 v[88:91], v[152:155], v[190:193], v[88:91]
	v_mfma_f32_16x16x32_bf16 v[84:87], v[144:147], v[198:201], v[84:87]
	v_mfma_f32_16x16x32_bf16 v[80:83], v[152:155], v[198:201], v[80:83]
	v_mfma_f32_16x16x32_bf16 v[76:79], v[144:147], v[206:209], v[76:79]
	v_mfma_f32_16x16x32_bf16 v[72:75], v[152:155], v[206:209], v[72:75]
	v_mfma_f32_16x16x32_bf16 v[64:67], v[144:147], v[214:217], v[64:67]
	v_mfma_f32_16x16x32_bf16 v[56:59], v[152:155], v[214:217], v[56:59]
	v_mfma_f32_16x16x32_bf16 v[92:95], v[148:151], v[194:197], v[92:95]
	v_mfma_f32_16x16x32_bf16 v[88:91], v[170:173], v[194:197], v[88:91]
	v_mfma_f32_16x16x32_bf16 v[84:87], v[148:151], v[202:205], v[84:87]
	v_mfma_f32_16x16x32_bf16 v[80:83], v[170:173], v[202:205], v[80:83]
	v_mfma_f32_16x16x32_bf16 v[76:79], v[148:151], v[210:213], v[76:79]
	v_mfma_f32_16x16x32_bf16 v[72:75], v[170:173], v[210:213], v[72:75]
	v_mfma_f32_16x16x32_bf16 v[64:67], v[148:151], v[218:221], v[64:67]
	v_mfma_f32_16x16x32_bf16 v[56:59], v[170:173], v[218:221], v[56:59]
	v_mfma_f32_16x16x32_bf16 v[28:31], v[174:177], v[190:193], v[28:31]
	v_mfma_f32_16x16x32_bf16 v[24:27], v[182:185], v[190:193], v[24:27]
	v_mfma_f32_16x16x32_bf16 v[20:23], v[174:177], v[198:201], v[20:23]
	v_mfma_f32_16x16x32_bf16 v[16:19], v[182:185], v[198:201], v[16:19]
	v_mfma_f32_16x16x32_bf16 v[12:15], v[174:177], v[206:209], v[12:15]
	v_mfma_f32_16x16x32_bf16 v[8:11], v[182:185], v[206:209], v[8:11]
	v_mfma_f32_16x16x32_bf16 v[4:7], v[174:177], v[214:217], v[4:7]
	v_mfma_f32_16x16x32_bf16 v[0:3], v[182:185], v[214:217], v[0:3]
	v_mfma_f32_16x16x32_bf16 v[28:31], v[178:181], v[194:197], v[28:31]
	v_mfma_f32_16x16x32_bf16 v[24:27], v[186:189], v[194:197], v[24:27]
	v_mfma_f32_16x16x32_bf16 v[20:23], v[178:181], v[202:205], v[20:23]
	v_mfma_f32_16x16x32_bf16 v[16:19], v[186:189], v[202:205], v[16:19]
	v_mfma_f32_16x16x32_bf16 v[12:15], v[178:181], v[210:213], v[12:15]
	v_mfma_f32_16x16x32_bf16 v[8:11], v[186:189], v[210:213], v[8:11]
	v_mfma_f32_16x16x32_bf16 v[4:7], v[178:181], v[218:221], v[4:7]
	v_mfma_f32_16x16x32_bf16 v[0:3], v[186:189], v[218:221], v[0:3]
	s_setprio 0
	s_barrier
	s_add_u32 s18, s18, 0x100
	s_addc_u32 s19, s19, 0
	s_add_u32 s52, s52, 0x100
	s_addc_u32 s53, s53, 0
	s_cmp_ge_u32 s54, s50
	s_mov_b32 s20, s54
	s_cbranch_scc0 .LBB0_1827
	s_and_b64 vcc, exec, s[12:13]
	s_cbranch_vccz .LBB0_1830
	s_barrier
